# IDX phase: 4-query units pulled per wave from an atomic queue per blockIdx%8 group, largest first, instead of the static two-round split
# baseline (speedup 1.0000x reference)
; __device__ __forceinline__ void idx_unit(bf16* QB, float* SC, int* SEL, const float* qg, const float* kg, int b, int tp, LAS unsigned char* wl, int lane, bool do_norm) {
;     const int t = 4 * tp; const size_t rowbase = (size_t)b * SEQ; const size_t row = rowbase + t;
;     const int n = lane & 31, hi = lane >> 5;
;     const int ce = ((t >> 6) + 1) << 6;
;     if (ce > 256) {
;     ...
;     } else {
; #pragma unroll
;         for (int i = 0; i < 4; ++i) { const int p = lane + 64 * i; if (p < ce) {
; #pragma unroll
;             for (int a = 0; a < 4; ++a) SEL[(row + a) * 256 + p] = p; } }
; __global__ void __launch_bounds__(NWAVES * 64, 2) fwd_megakernel(Args args) {
;     ...
;                 const int per = SEQ / 4;
;                 for (int rep = 0; rep < REP_IDX; ++rep) for (int i = 0; i * ngw < NBATCH * per; ++i) { const int u = i * ngw + gw; if (u >= NBATCH * per) break;
;                     const int bb = u / per; int tp = u % per; if (i & 1) tp = per - 1 - tp;
.LBB0_230:
	v_readlane_b32 s0, v251, 10
	v_readlane_b32 s1, v251, 11
	v_readlane_b32 s3, v251, 14
	v_readlane_b32 s2, v254, 3
	v_mov_b32_e32 v1, 1
	s_nop 2
	s_and_b32 s3, s3, 7
	s_add_u32 s4, s3, 33
	s_lshl_b32 s4, s4, 8
	s_lshr_b32 s2, s2, 1
	s_lshl_b32 s2, s2, 2
	s_add_u32 s4, s4, s2
	s_add_u32 s4, s4, 8
	s_add_u32 s0, s0, s4
	s_addc_u32 s1, s1, 0
	s_mov_b64 s[4:5], exec
	s_mov_b64 exec, 1
	global_atomic_add v0, v183, v1, s[0:1] sc0
	s_mov_b64 exec, s[4:5]
	s_waitcnt vmcnt(0)
	v_readfirstlane_b32 s2, v0
	s_nop 3
	s_lshr_b32 s4, s2, 2
	s_lshl_b32 s4, s4, 3
	s_add_u32 s4, s4, s3
	s_sub_u32 s4, 0x3ff, s4
	s_and_b32 s5, s2, 3
	s_lshl_b32 s5, s5, 10
	s_or_b32 s3, s4, s5
	s_cmpk_lt_u32 s2, 0x200
	s_cselect_b32 s3, s3, 0x1000
	s_cmpk_gt_i32 s3, 0xfff
	s_mov_b64 s[0:1], -1
	s_cbranch_scc1 .LBB0_229
	s_ashr_i32 s0, s3, 31
	s_lshr_b32 s0, s0, 22
	s_add_i32 s1, s3, s0
	s_ashr_i32 s0, s1, 10
	s_and_b32 s1, s1, 0xfffffc00
	s_sub_i32 s1, s3, s1
	s_mov_b32 s2, 0
	s_sub_i32 s3, 0x3ff, s1
	s_cmp_eq_u32 s2, 0
	s_cselect_b32 s1, s1, s3
	s_lshl_b32 s7, s1, 2
	s_ashr_i32 s1, s0, 31
	s_lshl_b64 s[0:1], s[0:1], 12
	s_ashr_i32 s3, s7, 31
	s_add_u32 s2, s0, s7
	s_addc_u32 s79, s1, s3
	s_andn2_b32 s7, s7, 63
	s_add_i32 s6, s7, 64
	s_mov_b64 s[14:15], 0x2000
	s_movk_i32 s10, 0x2000
	s_mov_b32 s3, s79
	s_cmpk_gt_i32 s7, 0xff
	s_mov_b64 s[4:5], -1
	s_cbranch_scc1 .LBB0_241
	v_cmp_gt_i32_e32 vcc, s6, v96
	s_and_saveexec_b64 s[4:5], vcc
	s_cbranch_execz .LBB0_236
	s_lshl_b64 s[8:9], s[2:3], 10
	v_lshl_add_u64 v[0:1], v[98:99], 0, s[8:9]
	global_store_dword v[0:1], v96, off
	global_store_dword v[0:1], v96, off offset:1024
	global_store_dword v[0:1], v96, off offset:2048
	global_store_dword v[0:1], v96, off offset:3072
	s_or_b64 exec, exec, s[4:5]
	v_cmp_gt_i32_e32 vcc, s7, v96
	s_and_saveexec_b64 s[4:5], vcc
	s_cbranch_execnz .LBB0_237

; __device__ __forceinline__ unsigned pk2(float lo, float hi) { return pg8::cvt_pk_bf16(lo, hi); }
; __device__ __forceinline__ void idx_unit(bf16* QB, float* SC, int* SEL, const float* qg, const float* kg, int b, int tp, LAS unsigned char* wl, int lane, bool do_norm) {
;     ...
;     if (!do_norm) return;
;     const int lg = lane >> 4, li = lane & 15;
; #pragma unroll 1
;     for (int a = 0; a < 4; ++a)
; #pragma unroll 1
;         for (int p = 0; p < 5; ++p) {
;             const int col = (p < 4) ? (CQ + (4 * p + lg) * 128) : (CK + lg * 128);
;             bf16* ptr = QB + (row + a) * NBP + col + 8 * li;
;             const u32x4 w = *(const u32x4*)ptr;
;             float v[8] = {bflo(w.x), bfhi(w.x), bflo(w.y), bfhi(w.y), bflo(w.z), bfhi(w.z), bflo(w.w), bfhi(w.w)};
;             float s = 0.f;
; #pragma unroll
;             for (int e = 0; e < 8; ++e) s += v[e] * v[e];
;             s += __shfl_xor(s, 1); s += __shfl_xor(s, 2); s += __shfl_xor(s, 4); s += __shfl_xor(s, 8);
;             const float rstd = (1.0f / sqrtf(s * (1.f / 128.f) + RMS_EPS)) * ((p < 4) ? C2 : 1.f);
;             const float* gp = ((p < 4) ? qg : kg) + 8 * li;
;             const f32x4 g0 = *(const f32x4*)gp, g1 = *(const f32x4*)(gp + 4);
;             u32x4 o; o.x = pk2(v[0] * rstd * g0.x, v[1] * rstd * g0.y); o.y = pk2(v[2] * rstd * g0.z, v[3] * rstd * g0.w);
;             o.z = pk2(v[4] * rstd * g1.x, v[5] * rstd * g1.y); o.w = pk2(v[6] * rstd * g1.z, v[7] * rstd * g1.w);
;             *(u32x4*)ptr = o;
;         }
.LBB0_561:
	v_readlane_b32 s66, v253, 47
	v_readlane_b32 s84, v253, 49
	v_readlane_b32 s58, v253, 44
	v_readlane_b32 s67, v253, 48
	v_readlane_b32 s85, v253, 50
	v_readlane_b32 s88, v253, 59
	s_mov_b32 s3, 0
	v_readlane_b32 s59, v253, 45
	v_readlane_b32 s64, v253, 46
	v_readlane_b32 s67, v253, 55
	v_readlane_b32 s85, v253, 56
	v_readlane_b32 s86, v253, 57
	v_readlane_b32 s87, v253, 58
	v_readlane_b32 s89, v253, 60
	s_movk_i32 s92, 0x3000
	s_movk_i32 s93, 0x5a
	s_mov_b32 s94, 0xff800000
	v_readlane_b32 s49, v254, 6
	v_readlane_b32 s11, v250, 33
	s_add_u32 s0, s80, s76
	s_addc_u32 s1, s81, s77
	global_load_dwordx4 v[222:225], v105, s[0:1] offset:16
	global_load_dwordx4 v[218:221], v105, s[0:1]
	s_add_u32 s0, s82, s76
	s_addc_u32 s1, s83, s77
	global_load_dwordx4 v[230:233], v105, s[0:1] offset:16
	global_load_dwordx4 v[226:229], v105, s[0:1]
	s_add_u32 s0, s2, 0
	s_addc_u32 s1, s79, 0
	s_mul_i32 s4, s1, 0x2200
	v_mad_u64_u32 v[0:1], s[0:1], s0, v212, v[118:119]
	v_add_u32_e32 v1, s4, v1
	v_mov_b32_e32 v2, v216
	v_ashrrev_i32_e32 v3, 31, v2
	v_lshl_add_u64 v[14:15], v[2:3], 1, v[0:1]
	global_load_dwordx4 v[16:19], v[14:15], off
	v_add_u32_e32 v2, 0x200, v216
	v_ashrrev_i32_e32 v3, 31, v2
	v_lshl_add_u64 v[14:15], v[2:3], 1, v[0:1]
	global_load_dwordx4 v[20:23], v[14:15], off
	v_add_u32_e32 v2, 0x400, v216
	v_ashrrev_i32_e32 v3, 31, v2
	v_lshl_add_u64 v[14:15], v[2:3], 1, v[0:1]
	global_load_dwordx4 v[24:27], v[14:15], off
	v_add_u32_e32 v2, 0x600, v216
	v_ashrrev_i32_e32 v3, 31, v2
	v_lshl_add_u64 v[14:15], v[2:3], 1, v[0:1]
	global_load_dwordx4 v[28:31], v[14:15], off
	v_add_u32_e32 v2, 0x800, v216
	v_ashrrev_i32_e32 v3, 31, v2
	v_lshl_add_u64 v[14:15], v[2:3], 1, v[0:1]
	global_load_dwordx4 v[32:35], v[14:15], off
	s_add_u32 s0, s2, 1
	s_addc_u32 s1, s79, 0
	s_mul_i32 s4, s1, 0x2200
	v_mad_u64_u32 v[0:1], s[0:1], s0, v212, v[118:119]
	v_add_u32_e32 v1, s4, v1
	v_mov_b32_e32 v2, v216
	v_ashrrev_i32_e32 v3, 31, v2
	v_lshl_add_u64 v[14:15], v[2:3], 1, v[0:1]
	global_load_dwordx4 v[36:39], v[14:15], off
	v_add_u32_e32 v2, 0x200, v216
	v_ashrrev_i32_e32 v3, 31, v2
	v_lshl_add_u64 v[14:15], v[2:3], 1, v[0:1]
	global_load_dwordx4 v[40:43], v[14:15], off
	v_add_u32_e32 v2, 0x400, v216
	v_ashrrev_i32_e32 v3, 31, v2
	v_lshl_add_u64 v[14:15], v[2:3], 1, v[0:1]
	global_load_dwordx4 v[44:47], v[14:15], off
	v_add_u32_e32 v2, 0x600, v216
	v_ashrrev_i32_e32 v3, 31, v2
	v_lshl_add_u64 v[14:15], v[2:3], 1, v[0:1]
	global_load_dwordx4 v[48:51], v[14:15], off
	v_add_u32_e32 v2, 0x800, v216
	v_ashrrev_i32_e32 v3, 31, v2
	v_lshl_add_u64 v[14:15], v[2:3], 1, v[0:1]
	global_load_dwordx4 v[52:55], v[14:15], off
	s_add_u32 s0, s2, 2
	s_addc_u32 s1, s79, 0
	s_mul_i32 s4, s1, 0x2200
	v_mad_u64_u32 v[0:1], s[0:1], s0, v212, v[118:119]
	v_add_u32_e32 v1, s4, v1
	v_mov_b32_e32 v2, v216
	v_ashrrev_i32_e32 v3, 31, v2
	v_lshl_add_u64 v[14:15], v[2:3], 1, v[0:1]
	global_load_dwordx4 v[56:59], v[14:15], off
	v_add_u32_e32 v2, 0x200, v216
	v_ashrrev_i32_e32 v3, 31, v2
	v_lshl_add_u64 v[14:15], v[2:3], 1, v[0:1]
	global_load_dwordx4 v[60:63], v[14:15], off
	v_add_u32_e32 v2, 0x400, v216
	v_ashrrev_i32_e32 v3, 31, v2
	v_lshl_add_u64 v[14:15], v[2:3], 1, v[0:1]
	global_load_dwordx4 v[64:67], v[14:15], off
	v_add_u32_e32 v2, 0x600, v216
	v_ashrrev_i32_e32 v3, 31, v2
	v_lshl_add_u64 v[14:15], v[2:3], 1, v[0:1]
	global_load_dwordx4 v[68:71], v[14:15], off
	v_add_u32_e32 v2, 0x800, v216
	v_ashrrev_i32_e32 v3, 31, v2
	v_lshl_add_u64 v[14:15], v[2:3], 1, v[0:1]
	global_load_dwordx4 v[72:75], v[14:15], off
	s_add_u32 s0, s2, 3
	s_addc_u32 s1, s79, 0
	s_mul_i32 s4, s1, 0x2200
	v_mad_u64_u32 v[0:1], s[0:1], s0, v212, v[118:119]
	v_add_u32_e32 v1, s4, v1
	v_mov_b32_e32 v2, v216
	v_ashrrev_i32_e32 v3, 31, v2
	v_lshl_add_u64 v[14:15], v[2:3], 1, v[0:1]
	global_load_dwordx4 v[76:79], v[14:15], off
	v_add_u32_e32 v2, 0x200, v216
	v_ashrrev_i32_e32 v3, 31, v2
	v_lshl_add_u64 v[14:15], v[2:3], 1, v[0:1]
	global_load_dwordx4 v[80:83], v[14:15], off
	v_add_u32_e32 v2, 0x400, v216
	v_ashrrev_i32_e32 v3, 31, v2
	v_lshl_add_u64 v[14:15], v[2:3], 1, v[0:1]
	global_load_dwordx4 v[84:87], v[14:15], off
	v_add_u32_e32 v2, 0x600, v216
	v_ashrrev_i32_e32 v3, 31, v2
	v_lshl_add_u64 v[14:15], v[2:3], 1, v[0:1]
	global_load_dwordx4 v[88:91], v[14:15], off
	v_add_u32_e32 v2, 0x800, v216
	v_ashrrev_i32_e32 v3, 31, v2
	v_lshl_add_u64 v[14:15], v[2:3], 1, v[0:1]
	global_load_dwordx4 v[92:95], v[14:15], off
	s_add_u32 s0, s2, 0
	s_addc_u32 s1, s79, 0
	s_mul_i32 s4, s1, 0x2200
	v_mad_u64_u32 v[0:1], s[0:1], s0, v212, v[118:119]
	v_add_u32_e32 v1, s4, v1
	s_waitcnt vmcnt(19)
	v_mov_b32_e32 v217, v211
	v_lshlrev_b32_e32 v234, 16, v16
	v_and_b32_e32 v16, 0xffff0000, v16
	v_mul_f32_e32 v238, v16, v16
	v_lshlrev_b32_e32 v235, 16, v17
	v_fmac_f32_e32 v238, v234, v234
	v_and_b32_e32 v17, 0xffff0000, v17
	v_fmac_f32_e32 v238, v235, v235
	v_lshlrev_b32_e32 v236, 16, v18
	v_fmac_f32_e32 v238, v17, v17
	v_and_b32_e32 v18, 0xffff0000, v18
	v_fmac_f32_e32 v238, v236, v236
	v_lshlrev_b32_e32 v237, 16, v19
	v_fmac_f32_e32 v238, v18, v18
	v_and_b32_e32 v19, 0xffff0000, v19
	v_fmac_f32_e32 v238, v237, v237
	v_fmac_f32_e32 v238, v19, v19
	ds_bpermute_b32 v239, v204, v238
	s_waitcnt lgkmcnt(0)
	v_add_f32_e32 v238, v238, v239
	ds_bpermute_b32 v239, v205, v238
	s_waitcnt lgkmcnt(0)
	v_add_f32_e32 v238, v238, v239
	ds_bpermute_b32 v239, v214, v238
	s_waitcnt lgkmcnt(0)
	v_add_f32_e32 v238, v238, v239
	ds_bpermute_b32 v239, v215, v238
	s_waitcnt lgkmcnt(0)
; __device__ __forceinline__ unsigned pk2(float lo, float hi) { return pg8::cvt_pk_bf16(lo, hi); }
; __device__ __forceinline__ void idx_unit(bf16* QB, float* SC, int* SEL, const float* qg, const float* kg, int b, int tp, LAS unsigned char* wl, int lane, bool do_norm) {
;     ...
;             const u32x4 w = *(const u32x4*)ptr;
;             float v[8] = {bflo(w.x), bfhi(w.x), bflo(w.y), bfhi(w.y), bflo(w.z), bfhi(w.z), bflo(w.w), bfhi(w.w)};
;             float s = 0.f;
; #pragma unroll
;             for (int e = 0; e < 8; ++e) s += v[e] * v[e];
;             s += __shfl_xor(s, 1); s += __shfl_xor(s, 2); s += __shfl_xor(s, 4); s += __shfl_xor(s, 8);
;             const float rstd = (1.0f / sqrtf(s * (1.f / 128.f) + RMS_EPS)) * ((p < 4) ? C2 : 1.f);
;             const float* gp = ((p < 4) ? qg : kg) + 8 * li;
;             const f32x4 g0 = *(const f32x4*)gp, g1 = *(const f32x4*)(gp + 4);
;             u32x4 o; o.x = pk2(v[0] * rstd * g0.x, v[1] * rstd * g0.y); o.y = pk2(v[2] * rstd * g0.z, v[3] * rstd * g0.w);
;             o.z = pk2(v[4] * rstd * g1.x, v[5] * rstd * g1.y); o.w = pk2(v[6] * rstd * g1.z, v[7] * rstd * g1.w);
;             *(u32x4*)ptr = o;
;         }
	v_add_f32_e32 v238, v238, v239
	v_fmamk_f32 v238, v238, 0x3c000000, v208
	v_mul_f32_e32 v239, 0x4f800000, v238
	v_cmp_gt_f32_e32 vcc, s33, v238
	s_nop 1
	v_cndmask_b32_e32 v238, v238, v239, vcc
	v_sqrt_f32_e32 v239, v238
	s_nop 0
	v_add_u32_e32 v240, -1, v239
	v_add_u32_e32 v241, 1, v239
	v_fma_f32 v242, -v240, v239, v238
	v_fma_f32 v243, -v241, v239, v238
	v_cmp_ge_f32_e64 s[0:1], 0, v242
	s_nop 1
	v_cndmask_b32_e64 v239, v239, v240, s[0:1]
	v_cmp_lt_f32_e64 s[0:1], 0, v243
	s_nop 1
	v_cndmask_b32_e64 v239, v239, v241, s[0:1]
	v_mul_f32_e32 v240, 0x37800000, v239
	v_cndmask_b32_e32 v239, v239, v240, vcc
	v_cmp_class_f32_e32 vcc, v238, v209
	s_nop 1
	v_cndmask_b32_e32 v238, v239, v238, vcc
	v_div_scale_f32 v239, s[0:1], v238, v238, 1.0
	v_rcp_f32_e32 v241, v239
	v_div_scale_f32 v240, vcc, 1.0, v238, 1.0
	v_fma_f32 v242, -v239, v241, 1.0
	v_fmac_f32_e32 v241, v242, v241
	v_mul_f32_e32 v242, v240, v241
	v_fma_f32 v243, -v239, v242, v240
	v_fmac_f32_e32 v242, v243, v241
	v_fma_f32 v239, -v239, v242, v240
	v_div_fmas_f32 v239, v239, v241, v242
	v_div_fixup_f32 v238, v239, v238, 1.0
	v_mul_f32_e32 v217, v217, v238
	v_mul_f32_e32 v16, v217, v16
	v_mul_f32_e32 v17, v217, v17
	v_mul_f32_e32 v18, v217, v18
	v_mul_f32_e32 v19, v217, v19
	v_mul_f32_e32 v234, v217, v234
	v_mul_f32_e32 v235, v217, v235
	v_mul_f32_e32 v236, v217, v236
	v_mul_f32_e32 v237, v217, v237
	v_mul_f32_e32 v16, v219, v16
	v_mul_f32_e32 v17, v221, v17
	v_mul_f32_e32 v18, v223, v18
	v_mul_f32_e32 v19, v225, v19
	v_mul_f32_e32 v244, v218, v234
	v_mul_f32_e32 v245, v220, v235
	v_mul_f32_e32 v246, v222, v236
	v_mul_f32_e32 v247, v224, v237
	v_cvt_pk_bf16_f32 v16, v244, v16
	v_cvt_pk_bf16_f32 v17, v245, v17
	v_cvt_pk_bf16_f32 v18, v246, v18
	v_cvt_pk_bf16_f32 v19, v247, v19
	v_mov_b32_e32 v2, v216
	v_ashrrev_i32_e32 v3, 31, v2
	v_lshl_add_u64 v[14:15], v[2:3], 1, v[0:1]
	global_store_dwordx4 v[14:15], v[16:19], off
	s_waitcnt vmcnt(19)
	v_mov_b32_e32 v217, v211
	v_lshlrev_b32_e32 v234, 16, v20
	v_and_b32_e32 v20, 0xffff0000, v20
	v_mul_f32_e32 v238, v20, v20
	v_lshlrev_b32_e32 v235, 16, v21
	v_fmac_f32_e32 v238, v234, v234
	v_and_b32_e32 v21, 0xffff0000, v21
	v_fmac_f32_e32 v238, v235, v235
	v_lshlrev_b32_e32 v236, 16, v22
	v_fmac_f32_e32 v238, v21, v21
	v_and_b32_e32 v22, 0xffff0000, v22
	v_fmac_f32_e32 v238, v236, v236
	v_lshlrev_b32_e32 v237, 16, v23
	v_fmac_f32_e32 v238, v22, v22
	v_and_b32_e32 v23, 0xffff0000, v23
	v_fmac_f32_e32 v238, v237, v237
	v_fmac_f32_e32 v238, v23, v23
	ds_bpermute_b32 v239, v204, v238
	s_waitcnt lgkmcnt(0)
	v_add_f32_e32 v238, v238, v239
	ds_bpermute_b32 v239, v205, v238
	s_waitcnt lgkmcnt(0)
	v_add_f32_e32 v238, v238, v239
	ds_bpermute_b32 v239, v214, v238
	s_waitcnt lgkmcnt(0)
	v_add_f32_e32 v238, v238, v239
	ds_bpermute_b32 v239, v215, v238
	s_waitcnt lgkmcnt(0)
	v_add_f32_e32 v238, v238, v239
	v_fmamk_f32 v238, v238, 0x3c000000, v208
	v_mul_f32_e32 v239, 0x4f800000, v238
	v_cmp_gt_f32_e32 vcc, s33, v238
	s_nop 1
	v_cndmask_b32_e32 v238, v238, v239, vcc
	v_sqrt_f32_e32 v239, v238
	s_nop 0
	v_add_u32_e32 v240, -1, v239
	v_add_u32_e32 v241, 1, v239
	v_fma_f32 v242, -v240, v239, v238
	v_fma_f32 v243, -v241, v239, v238
	v_cmp_ge_f32_e64 s[0:1], 0, v242
	s_nop 1
	v_cndmask_b32_e64 v239, v239, v240, s[0:1]
	v_cmp_lt_f32_e64 s[0:1], 0, v243
	s_nop 1
	v_cndmask_b32_e64 v239, v239, v241, s[0:1]
	v_mul_f32_e32 v240, 0x37800000, v239
	v_cndmask_b32_e32 v239, v239, v240, vcc
	v_cmp_class_f32_e32 vcc, v238, v209
	s_nop 1
	v_cndmask_b32_e32 v238, v239, v238, vcc
	v_div_scale_f32 v239, s[0:1], v238, v238, 1.0
	v_rcp_f32_e32 v241, v239
	v_div_scale_f32 v240, vcc, 1.0, v238, 1.0
	v_fma_f32 v242, -v239, v241, 1.0
	v_fmac_f32_e32 v241, v242, v241
	v_mul_f32_e32 v242, v240, v241
	v_fma_f32 v243, -v239, v242, v240
	v_fmac_f32_e32 v242, v243, v241
	v_fma_f32 v239, -v239, v242, v240
	v_div_fmas_f32 v239, v239, v241, v242
	v_div_fixup_f32 v238, v239, v238, 1.0
	v_mul_f32_e32 v217, v217, v238
	v_mul_f32_e32 v20, v217, v20
	v_mul_f32_e32 v21, v217, v21
	v_mul_f32_e32 v22, v217, v22
	v_mul_f32_e32 v23, v217, v23
	v_mul_f32_e32 v234, v217, v234
	v_mul_f32_e32 v235, v217, v235
	v_mul_f32_e32 v236, v217, v236
	v_mul_f32_e32 v237, v217, v237
	v_mul_f32_e32 v20, v219, v20
	v_mul_f32_e32 v21, v221, v21
	v_mul_f32_e32 v22, v223, v22
	v_mul_f32_e32 v23, v225, v23
	v_mul_f32_e32 v244, v218, v234
	v_mul_f32_e32 v245, v220, v235
	v_mul_f32_e32 v246, v222, v236
	v_mul_f32_e32 v247, v224, v237
	v_cvt_pk_bf16_f32 v20, v244, v20
	v_cvt_pk_bf16_f32 v21, v245, v21
	v_cvt_pk_bf16_f32 v22, v246, v22
	v_cvt_pk_bf16_f32 v23, v247, v23
	v_add_u32_e32 v2, 0x200, v216
	v_ashrrev_i32_e32 v3, 31, v2
	v_lshl_add_u64 v[14:15], v[2:3], 1, v[0:1]
	global_store_dwordx4 v[14:15], v[20:23], off
	s_waitcnt vmcnt(19)
	v_mov_b32_e32 v217, v211
	v_lshlrev_b32_e32 v234, 16, v24
	v_and_b32_e32 v24, 0xffff0000, v24
	v_mul_f32_e32 v238, v24, v24
	v_lshlrev_b32_e32 v235, 16, v25
	v_fmac_f32_e32 v238, v234, v234
	v_and_b32_e32 v25, 0xffff0000, v25
	v_fmac_f32_e32 v238, v235, v235
	v_lshlrev_b32_e32 v236, 16, v26
	v_fmac_f32_e32 v238, v25, v25
	v_and_b32_e32 v26, 0xffff0000, v26
	v_fmac_f32_e32 v238, v236, v236
	v_lshlrev_b32_e32 v237, 16, v27
	v_fmac_f32_e32 v238, v26, v26
	v_and_b32_e32 v27, 0xffff0000, v27
	v_fmac_f32_e32 v238, v237, v237
	v_fmac_f32_e32 v238, v27, v27
	ds_bpermute_b32 v239, v204, v238
	s_waitcnt lgkmcnt(0)
	v_add_f32_e32 v238, v238, v239
	ds_bpermute_b32 v239, v205, v238
	s_waitcnt lgkmcnt(0)
	v_add_f32_e32 v238, v238, v239
	ds_bpermute_b32 v239, v214, v238
	s_waitcnt lgkmcnt(0)
	v_add_f32_e32 v238, v238, v239
	ds_bpermute_b32 v239, v215, v238
	s_waitcnt lgkmcnt(0)
; __device__ __forceinline__ unsigned pk2(float lo, float hi) { return pg8::cvt_pk_bf16(lo, hi); }
; __device__ __forceinline__ void idx_unit(bf16* QB, float* SC, int* SEL, const float* qg, const float* kg, int b, int tp, LAS unsigned char* wl, int lane, bool do_norm) {
;     ...
;             const u32x4 w = *(const u32x4*)ptr;
;             float v[8] = {bflo(w.x), bfhi(w.x), bflo(w.y), bfhi(w.y), bflo(w.z), bfhi(w.z), bflo(w.w), bfhi(w.w)};
;             float s = 0.f;
; #pragma unroll
;             for (int e = 0; e < 8; ++e) s += v[e] * v[e];
;             s += __shfl_xor(s, 1); s += __shfl_xor(s, 2); s += __shfl_xor(s, 4); s += __shfl_xor(s, 8);
;             const float rstd = (1.0f / sqrtf(s * (1.f / 128.f) + RMS_EPS)) * ((p < 4) ? C2 : 1.f);
;             const float* gp = ((p < 4) ? qg : kg) + 8 * li;
;             const f32x4 g0 = *(const f32x4*)gp, g1 = *(const f32x4*)(gp + 4);
;             u32x4 o; o.x = pk2(v[0] * rstd * g0.x, v[1] * rstd * g0.y); o.y = pk2(v[2] * rstd * g0.z, v[3] * rstd * g0.w);
;             o.z = pk2(v[4] * rstd * g1.x, v[5] * rstd * g1.y); o.w = pk2(v[6] * rstd * g1.z, v[7] * rstd * g1.w);
;             *(u32x4*)ptr = o;
;         }
	v_add_f32_e32 v238, v238, v239
	v_fmamk_f32 v238, v238, 0x3c000000, v208
	v_mul_f32_e32 v239, 0x4f800000, v238
	v_cmp_gt_f32_e32 vcc, s33, v238
	s_nop 1
	v_cndmask_b32_e32 v238, v238, v239, vcc
	v_sqrt_f32_e32 v239, v238
	s_nop 0
	v_add_u32_e32 v240, -1, v239
	v_add_u32_e32 v241, 1, v239
	v_fma_f32 v242, -v240, v239, v238
	v_fma_f32 v243, -v241, v239, v238
	v_cmp_ge_f32_e64 s[0:1], 0, v242
	s_nop 1
	v_cndmask_b32_e64 v239, v239, v240, s[0:1]
	v_cmp_lt_f32_e64 s[0:1], 0, v243
	s_nop 1
	v_cndmask_b32_e64 v239, v239, v241, s[0:1]
	v_mul_f32_e32 v240, 0x37800000, v239
	v_cndmask_b32_e32 v239, v239, v240, vcc
	v_cmp_class_f32_e32 vcc, v238, v209
	s_nop 1
	v_cndmask_b32_e32 v238, v239, v238, vcc
	v_div_scale_f32 v239, s[0:1], v238, v238, 1.0
	v_rcp_f32_e32 v241, v239
	v_div_scale_f32 v240, vcc, 1.0, v238, 1.0
	v_fma_f32 v242, -v239, v241, 1.0
	v_fmac_f32_e32 v241, v242, v241
	v_mul_f32_e32 v242, v240, v241
	v_fma_f32 v243, -v239, v242, v240
	v_fmac_f32_e32 v242, v243, v241
	v_fma_f32 v239, -v239, v242, v240
	v_div_fmas_f32 v239, v239, v241, v242
	v_div_fixup_f32 v238, v239, v238, 1.0
	v_mul_f32_e32 v217, v217, v238
	v_mul_f32_e32 v24, v217, v24
	v_mul_f32_e32 v25, v217, v25
	v_mul_f32_e32 v26, v217, v26
	v_mul_f32_e32 v27, v217, v27
	v_mul_f32_e32 v234, v217, v234
	v_mul_f32_e32 v235, v217, v235
	v_mul_f32_e32 v236, v217, v236
	v_mul_f32_e32 v237, v217, v237
	v_mul_f32_e32 v24, v219, v24
	v_mul_f32_e32 v25, v221, v25
	v_mul_f32_e32 v26, v223, v26
	v_mul_f32_e32 v27, v225, v27
	v_mul_f32_e32 v244, v218, v234
	v_mul_f32_e32 v245, v220, v235
	v_mul_f32_e32 v246, v222, v236
	v_mul_f32_e32 v247, v224, v237
	v_cvt_pk_bf16_f32 v24, v244, v24
	v_cvt_pk_bf16_f32 v25, v245, v25
	v_cvt_pk_bf16_f32 v26, v246, v26
	v_cvt_pk_bf16_f32 v27, v247, v27
	v_add_u32_e32 v2, 0x400, v216
	v_ashrrev_i32_e32 v3, 31, v2
	v_lshl_add_u64 v[14:15], v[2:3], 1, v[0:1]
	global_store_dwordx4 v[14:15], v[24:27], off
	s_waitcnt vmcnt(19)
	v_mov_b32_e32 v217, v211
	v_lshlrev_b32_e32 v234, 16, v28
	v_and_b32_e32 v28, 0xffff0000, v28
	v_mul_f32_e32 v238, v28, v28
	v_lshlrev_b32_e32 v235, 16, v29
	v_fmac_f32_e32 v238, v234, v234
	v_and_b32_e32 v29, 0xffff0000, v29
	v_fmac_f32_e32 v238, v235, v235
	v_lshlrev_b32_e32 v236, 16, v30
	v_fmac_f32_e32 v238, v29, v29
	v_and_b32_e32 v30, 0xffff0000, v30
	v_fmac_f32_e32 v238, v236, v236
	v_lshlrev_b32_e32 v237, 16, v31
	v_fmac_f32_e32 v238, v30, v30
	v_and_b32_e32 v31, 0xffff0000, v31
	v_fmac_f32_e32 v238, v237, v237
	v_fmac_f32_e32 v238, v31, v31
	ds_bpermute_b32 v239, v204, v238
	s_waitcnt lgkmcnt(0)
	v_add_f32_e32 v238, v238, v239
	ds_bpermute_b32 v239, v205, v238
	s_waitcnt lgkmcnt(0)
	v_add_f32_e32 v238, v238, v239
	ds_bpermute_b32 v239, v214, v238
	s_waitcnt lgkmcnt(0)
	v_add_f32_e32 v238, v238, v239
	ds_bpermute_b32 v239, v215, v238
	s_waitcnt lgkmcnt(0)
	v_add_f32_e32 v238, v238, v239
	v_fmamk_f32 v238, v238, 0x3c000000, v208
	v_mul_f32_e32 v239, 0x4f800000, v238
	v_cmp_gt_f32_e32 vcc, s33, v238
	s_nop 1
	v_cndmask_b32_e32 v238, v238, v239, vcc
	v_sqrt_f32_e32 v239, v238
	s_nop 0
	v_add_u32_e32 v240, -1, v239
	v_add_u32_e32 v241, 1, v239
	v_fma_f32 v242, -v240, v239, v238
	v_fma_f32 v243, -v241, v239, v238
	v_cmp_ge_f32_e64 s[0:1], 0, v242
	s_nop 1
	v_cndmask_b32_e64 v239, v239, v240, s[0:1]
	v_cmp_lt_f32_e64 s[0:1], 0, v243
	s_nop 1
	v_cndmask_b32_e64 v239, v239, v241, s[0:1]
	v_mul_f32_e32 v240, 0x37800000, v239
	v_cndmask_b32_e32 v239, v239, v240, vcc
	v_cmp_class_f32_e32 vcc, v238, v209
	s_nop 1
	v_cndmask_b32_e32 v238, v239, v238, vcc
	v_div_scale_f32 v239, s[0:1], v238, v238, 1.0
	v_rcp_f32_e32 v241, v239
	v_div_scale_f32 v240, vcc, 1.0, v238, 1.0
	v_fma_f32 v242, -v239, v241, 1.0
	v_fmac_f32_e32 v241, v242, v241
	v_mul_f32_e32 v242, v240, v241
	v_fma_f32 v243, -v239, v242, v240
	v_fmac_f32_e32 v242, v243, v241
	v_fma_f32 v239, -v239, v242, v240
	v_div_fmas_f32 v239, v239, v241, v242
	v_div_fixup_f32 v238, v239, v238, 1.0
	v_mul_f32_e32 v217, v217, v238
	v_mul_f32_e32 v28, v217, v28
	v_mul_f32_e32 v29, v217, v29
	v_mul_f32_e32 v30, v217, v30
	v_mul_f32_e32 v31, v217, v31
	v_mul_f32_e32 v234, v217, v234
	v_mul_f32_e32 v235, v217, v235
	v_mul_f32_e32 v236, v217, v236
	v_mul_f32_e32 v237, v217, v237
	v_mul_f32_e32 v28, v219, v28
	v_mul_f32_e32 v29, v221, v29
	v_mul_f32_e32 v30, v223, v30
	v_mul_f32_e32 v31, v225, v31
	v_mul_f32_e32 v244, v218, v234
	v_mul_f32_e32 v245, v220, v235
	v_mul_f32_e32 v246, v222, v236
	v_mul_f32_e32 v247, v224, v237
	v_cvt_pk_bf16_f32 v28, v244, v28
	v_cvt_pk_bf16_f32 v29, v245, v29
	v_cvt_pk_bf16_f32 v30, v246, v30
	v_cvt_pk_bf16_f32 v31, v247, v31
	v_add_u32_e32 v2, 0x600, v216
	v_ashrrev_i32_e32 v3, 31, v2
	v_lshl_add_u64 v[14:15], v[2:3], 1, v[0:1]
	global_store_dwordx4 v[14:15], v[28:31], off
	s_waitcnt vmcnt(19)
	v_mov_b32_e32 v217, 1.0
	v_lshlrev_b32_e32 v234, 16, v32
	v_and_b32_e32 v32, 0xffff0000, v32
	v_mul_f32_e32 v238, v32, v32
	v_lshlrev_b32_e32 v235, 16, v33
	v_fmac_f32_e32 v238, v234, v234
	v_and_b32_e32 v33, 0xffff0000, v33
	v_fmac_f32_e32 v238, v235, v235
	v_lshlrev_b32_e32 v236, 16, v34
	v_fmac_f32_e32 v238, v33, v33
	v_and_b32_e32 v34, 0xffff0000, v34
	v_fmac_f32_e32 v238, v236, v236
	v_lshlrev_b32_e32 v237, 16, v35
	v_fmac_f32_e32 v238, v34, v34
	v_and_b32_e32 v35, 0xffff0000, v35
	v_fmac_f32_e32 v238, v237, v237
	v_fmac_f32_e32 v238, v35, v35
	ds_bpermute_b32 v239, v204, v238
	s_waitcnt lgkmcnt(0)
	v_add_f32_e32 v238, v238, v239
	ds_bpermute_b32 v239, v205, v238
	s_waitcnt lgkmcnt(0)
	v_add_f32_e32 v238, v238, v239
	ds_bpermute_b32 v239, v214, v238
	s_waitcnt lgkmcnt(0)
	v_add_f32_e32 v238, v238, v239
	ds_bpermute_b32 v239, v215, v238
	s_waitcnt lgkmcnt(0)
; __device__ __forceinline__ unsigned pk2(float lo, float hi) { return pg8::cvt_pk_bf16(lo, hi); }
; __device__ __forceinline__ void idx_unit(bf16* QB, float* SC, int* SEL, const float* qg, const float* kg, int b, int tp, LAS unsigned char* wl, int lane, bool do_norm) {
;     ...
;             const u32x4 w = *(const u32x4*)ptr;
;             float v[8] = {bflo(w.x), bfhi(w.x), bflo(w.y), bfhi(w.y), bflo(w.z), bfhi(w.z), bflo(w.w), bfhi(w.w)};
;             float s = 0.f;
; #pragma unroll
;             for (int e = 0; e < 8; ++e) s += v[e] * v[e];
;             s += __shfl_xor(s, 1); s += __shfl_xor(s, 2); s += __shfl_xor(s, 4); s += __shfl_xor(s, 8);
;             const float rstd = (1.0f / sqrtf(s * (1.f / 128.f) + RMS_EPS)) * ((p < 4) ? C2 : 1.f);
;             const float* gp = ((p < 4) ? qg : kg) + 8 * li;
;             const f32x4 g0 = *(const f32x4*)gp, g1 = *(const f32x4*)(gp + 4);
;             u32x4 o; o.x = pk2(v[0] * rstd * g0.x, v[1] * rstd * g0.y); o.y = pk2(v[2] * rstd * g0.z, v[3] * rstd * g0.w);
;             o.z = pk2(v[4] * rstd * g1.x, v[5] * rstd * g1.y); o.w = pk2(v[6] * rstd * g1.z, v[7] * rstd * g1.w);
;             *(u32x4*)ptr = o;
;         }
	v_add_f32_e32 v238, v238, v239
	v_fmamk_f32 v238, v238, 0x3c000000, v208
	v_mul_f32_e32 v239, 0x4f800000, v238
	v_cmp_gt_f32_e32 vcc, s33, v238
	s_nop 1
	v_cndmask_b32_e32 v238, v238, v239, vcc
	v_sqrt_f32_e32 v239, v238
	s_nop 0
	v_add_u32_e32 v240, -1, v239
	v_add_u32_e32 v241, 1, v239
	v_fma_f32 v242, -v240, v239, v238
	v_fma_f32 v243, -v241, v239, v238
	v_cmp_ge_f32_e64 s[0:1], 0, v242
	s_nop 1
	v_cndmask_b32_e64 v239, v239, v240, s[0:1]
	v_cmp_lt_f32_e64 s[0:1], 0, v243
	s_nop 1
	v_cndmask_b32_e64 v239, v239, v241, s[0:1]
	v_mul_f32_e32 v240, 0x37800000, v239
	v_cndmask_b32_e32 v239, v239, v240, vcc
	v_cmp_class_f32_e32 vcc, v238, v209
	s_nop 1
	v_cndmask_b32_e32 v238, v239, v238, vcc
	v_div_scale_f32 v239, s[0:1], v238, v238, 1.0
	v_rcp_f32_e32 v241, v239
	v_div_scale_f32 v240, vcc, 1.0, v238, 1.0
	v_fma_f32 v242, -v239, v241, 1.0
	v_fmac_f32_e32 v241, v242, v241
	v_mul_f32_e32 v242, v240, v241
	v_fma_f32 v243, -v239, v242, v240
	v_fmac_f32_e32 v242, v243, v241
	v_fma_f32 v239, -v239, v242, v240
	v_div_fmas_f32 v239, v239, v241, v242
	v_div_fixup_f32 v238, v239, v238, 1.0
	v_mul_f32_e32 v217, v217, v238
	v_mul_f32_e32 v32, v217, v32
	v_mul_f32_e32 v33, v217, v33
	v_mul_f32_e32 v34, v217, v34
	v_mul_f32_e32 v35, v217, v35
	v_mul_f32_e32 v234, v217, v234
	v_mul_f32_e32 v235, v217, v235
	v_mul_f32_e32 v236, v217, v236
	v_mul_f32_e32 v237, v217, v237
	v_mul_f32_e32 v32, v227, v32
	v_mul_f32_e32 v33, v229, v33
	v_mul_f32_e32 v34, v231, v34
	v_mul_f32_e32 v35, v233, v35
	v_mul_f32_e32 v244, v226, v234
	v_mul_f32_e32 v245, v228, v235
	v_mul_f32_e32 v246, v230, v236
	v_mul_f32_e32 v247, v232, v237
	v_cvt_pk_bf16_f32 v32, v244, v32
	v_cvt_pk_bf16_f32 v33, v245, v33
	v_cvt_pk_bf16_f32 v34, v246, v34
	v_cvt_pk_bf16_f32 v35, v247, v35
	v_add_u32_e32 v2, 0x800, v216
	v_ashrrev_i32_e32 v3, 31, v2
	v_lshl_add_u64 v[14:15], v[2:3], 1, v[0:1]
	global_store_dwordx4 v[14:15], v[32:35], off
	s_add_u32 s0, s2, 1
	s_addc_u32 s1, s79, 0
	s_mul_i32 s4, s1, 0x2200
	v_mad_u64_u32 v[0:1], s[0:1], s0, v212, v[118:119]
	v_add_u32_e32 v1, s4, v1
	s_waitcnt vmcnt(19)
	v_mov_b32_e32 v217, v211
	v_lshlrev_b32_e32 v234, 16, v36
	v_and_b32_e32 v36, 0xffff0000, v36
	v_mul_f32_e32 v238, v36, v36
	v_lshlrev_b32_e32 v235, 16, v37
	v_fmac_f32_e32 v238, v234, v234
	v_and_b32_e32 v37, 0xffff0000, v37
	v_fmac_f32_e32 v238, v235, v235
	v_lshlrev_b32_e32 v236, 16, v38
	v_fmac_f32_e32 v238, v37, v37
	v_and_b32_e32 v38, 0xffff0000, v38
	v_fmac_f32_e32 v238, v236, v236
	v_lshlrev_b32_e32 v237, 16, v39
	v_fmac_f32_e32 v238, v38, v38
	v_and_b32_e32 v39, 0xffff0000, v39
	v_fmac_f32_e32 v238, v237, v237
	v_fmac_f32_e32 v238, v39, v39
	ds_bpermute_b32 v239, v204, v238
	s_waitcnt lgkmcnt(0)
	v_add_f32_e32 v238, v238, v239
	ds_bpermute_b32 v239, v205, v238
	s_waitcnt lgkmcnt(0)
	v_add_f32_e32 v238, v238, v239
	ds_bpermute_b32 v239, v214, v238
	s_waitcnt lgkmcnt(0)
	v_add_f32_e32 v238, v238, v239
	ds_bpermute_b32 v239, v215, v238
	s_waitcnt lgkmcnt(0)
	v_add_f32_e32 v238, v238, v239
	v_fmamk_f32 v238, v238, 0x3c000000, v208
	v_mul_f32_e32 v239, 0x4f800000, v238
	v_cmp_gt_f32_e32 vcc, s33, v238
	s_nop 1
	v_cndmask_b32_e32 v238, v238, v239, vcc
	v_sqrt_f32_e32 v239, v238
	s_nop 0
	v_add_u32_e32 v240, -1, v239
	v_add_u32_e32 v241, 1, v239
	v_fma_f32 v242, -v240, v239, v238
	v_fma_f32 v243, -v241, v239, v238
	v_cmp_ge_f32_e64 s[0:1], 0, v242
	s_nop 1
	v_cndmask_b32_e64 v239, v239, v240, s[0:1]
	v_cmp_lt_f32_e64 s[0:1], 0, v243
	s_nop 1
	v_cndmask_b32_e64 v239, v239, v241, s[0:1]
	v_mul_f32_e32 v240, 0x37800000, v239
	v_cndmask_b32_e32 v239, v239, v240, vcc
	v_cmp_class_f32_e32 vcc, v238, v209
	s_nop 1
	v_cndmask_b32_e32 v238, v239, v238, vcc
	v_div_scale_f32 v239, s[0:1], v238, v238, 1.0
	v_rcp_f32_e32 v241, v239
	v_div_scale_f32 v240, vcc, 1.0, v238, 1.0
	v_fma_f32 v242, -v239, v241, 1.0
	v_fmac_f32_e32 v241, v242, v241
	v_mul_f32_e32 v242, v240, v241
	v_fma_f32 v243, -v239, v242, v240
	v_fmac_f32_e32 v242, v243, v241
	v_fma_f32 v239, -v239, v242, v240
	v_div_fmas_f32 v239, v239, v241, v242
	v_div_fixup_f32 v238, v239, v238, 1.0
	v_mul_f32_e32 v217, v217, v238
	v_mul_f32_e32 v36, v217, v36
	v_mul_f32_e32 v37, v217, v37
	v_mul_f32_e32 v38, v217, v38
	v_mul_f32_e32 v39, v217, v39
	v_mul_f32_e32 v234, v217, v234
	v_mul_f32_e32 v235, v217, v235
	v_mul_f32_e32 v236, v217, v236
	v_mul_f32_e32 v237, v217, v237
	v_mul_f32_e32 v36, v219, v36
	v_mul_f32_e32 v37, v221, v37
	v_mul_f32_e32 v38, v223, v38
	v_mul_f32_e32 v39, v225, v39
	v_mul_f32_e32 v244, v218, v234
	v_mul_f32_e32 v245, v220, v235
	v_mul_f32_e32 v246, v222, v236
	v_mul_f32_e32 v247, v224, v237
	v_cvt_pk_bf16_f32 v36, v244, v36
	v_cvt_pk_bf16_f32 v37, v245, v37
	v_cvt_pk_bf16_f32 v38, v246, v38
	v_cvt_pk_bf16_f32 v39, v247, v39
	v_mov_b32_e32 v2, v216
	v_ashrrev_i32_e32 v3, 31, v2
	v_lshl_add_u64 v[14:15], v[2:3], 1, v[0:1]
	global_store_dwordx4 v[14:15], v[36:39], off
	s_waitcnt vmcnt(19)
	v_mov_b32_e32 v217, v211
	v_lshlrev_b32_e32 v234, 16, v40
	v_and_b32_e32 v40, 0xffff0000, v40
	v_mul_f32_e32 v238, v40, v40
	v_lshlrev_b32_e32 v235, 16, v41
	v_fmac_f32_e32 v238, v234, v234
	v_and_b32_e32 v41, 0xffff0000, v41
	v_fmac_f32_e32 v238, v235, v235
	v_lshlrev_b32_e32 v236, 16, v42
	v_fmac_f32_e32 v238, v41, v41
	v_and_b32_e32 v42, 0xffff0000, v42
	v_fmac_f32_e32 v238, v236, v236
	v_lshlrev_b32_e32 v237, 16, v43
	v_fmac_f32_e32 v238, v42, v42
	v_and_b32_e32 v43, 0xffff0000, v43
	v_fmac_f32_e32 v238, v237, v237
	v_fmac_f32_e32 v238, v43, v43
	ds_bpermute_b32 v239, v204, v238
	s_waitcnt lgkmcnt(0)
	v_add_f32_e32 v238, v238, v239
	ds_bpermute_b32 v239, v205, v238
	s_waitcnt lgkmcnt(0)
	v_add_f32_e32 v238, v238, v239
	ds_bpermute_b32 v239, v214, v238
	s_waitcnt lgkmcnt(0)
; __device__ __forceinline__ unsigned pk2(float lo, float hi) { return pg8::cvt_pk_bf16(lo, hi); }
; __device__ __forceinline__ void idx_unit(bf16* QB, float* SC, int* SEL, const float* qg, const float* kg, int b, int tp, LAS unsigned char* wl, int lane, bool do_norm) {
;     ...
;             const u32x4 w = *(const u32x4*)ptr;
;             float v[8] = {bflo(w.x), bfhi(w.x), bflo(w.y), bfhi(w.y), bflo(w.z), bfhi(w.z), bflo(w.w), bfhi(w.w)};
;             float s = 0.f;
; #pragma unroll
;             for (int e = 0; e < 8; ++e) s += v[e] * v[e];
;             s += __shfl_xor(s, 1); s += __shfl_xor(s, 2); s += __shfl_xor(s, 4); s += __shfl_xor(s, 8);
;             const float rstd = (1.0f / sqrtf(s * (1.f / 128.f) + RMS_EPS)) * ((p < 4) ? C2 : 1.f);
;             const float* gp = ((p < 4) ? qg : kg) + 8 * li;
;             const f32x4 g0 = *(const f32x4*)gp, g1 = *(const f32x4*)(gp + 4);
;             u32x4 o; o.x = pk2(v[0] * rstd * g0.x, v[1] * rstd * g0.y); o.y = pk2(v[2] * rstd * g0.z, v[3] * rstd * g0.w);
;             o.z = pk2(v[4] * rstd * g1.x, v[5] * rstd * g1.y); o.w = pk2(v[6] * rstd * g1.z, v[7] * rstd * g1.w);
;             *(u32x4*)ptr = o;
;         }
	v_add_f32_e32 v238, v238, v239
	ds_bpermute_b32 v239, v215, v238
	s_waitcnt lgkmcnt(0)
	v_add_f32_e32 v238, v238, v239
	v_fmamk_f32 v238, v238, 0x3c000000, v208
	v_mul_f32_e32 v239, 0x4f800000, v238
	v_cmp_gt_f32_e32 vcc, s33, v238
	s_nop 1
	v_cndmask_b32_e32 v238, v238, v239, vcc
	v_sqrt_f32_e32 v239, v238
	s_nop 0
	v_add_u32_e32 v240, -1, v239
	v_add_u32_e32 v241, 1, v239
	v_fma_f32 v242, -v240, v239, v238
	v_fma_f32 v243, -v241, v239, v238
	v_cmp_ge_f32_e64 s[0:1], 0, v242
	s_nop 1
	v_cndmask_b32_e64 v239, v239, v240, s[0:1]
	v_cmp_lt_f32_e64 s[0:1], 0, v243
	s_nop 1
	v_cndmask_b32_e64 v239, v239, v241, s[0:1]
	v_mul_f32_e32 v240, 0x37800000, v239
	v_cndmask_b32_e32 v239, v239, v240, vcc
	v_cmp_class_f32_e32 vcc, v238, v209
	s_nop 1
	v_cndmask_b32_e32 v238, v239, v238, vcc
	v_div_scale_f32 v239, s[0:1], v238, v238, 1.0
	v_rcp_f32_e32 v241, v239
	v_div_scale_f32 v240, vcc, 1.0, v238, 1.0
	v_fma_f32 v242, -v239, v241, 1.0
	v_fmac_f32_e32 v241, v242, v241
	v_mul_f32_e32 v242, v240, v241
	v_fma_f32 v243, -v239, v242, v240
	v_fmac_f32_e32 v242, v243, v241
	v_fma_f32 v239, -v239, v242, v240
	v_div_fmas_f32 v239, v239, v241, v242
	v_div_fixup_f32 v238, v239, v238, 1.0
	v_mul_f32_e32 v217, v217, v238
	v_mul_f32_e32 v40, v217, v40
	v_mul_f32_e32 v41, v217, v41
	v_mul_f32_e32 v42, v217, v42
	v_mul_f32_e32 v43, v217, v43
	v_mul_f32_e32 v234, v217, v234
	v_mul_f32_e32 v235, v217, v235
	v_mul_f32_e32 v236, v217, v236
	v_mul_f32_e32 v237, v217, v237
	v_mul_f32_e32 v40, v219, v40
	v_mul_f32_e32 v41, v221, v41
	v_mul_f32_e32 v42, v223, v42
	v_mul_f32_e32 v43, v225, v43
	v_mul_f32_e32 v244, v218, v234
	v_mul_f32_e32 v245, v220, v235
	v_mul_f32_e32 v246, v222, v236
	v_mul_f32_e32 v247, v224, v237
	v_cvt_pk_bf16_f32 v40, v244, v40
	v_cvt_pk_bf16_f32 v41, v245, v41
	v_cvt_pk_bf16_f32 v42, v246, v42
	v_cvt_pk_bf16_f32 v43, v247, v43
	v_add_u32_e32 v2, 0x200, v216
	v_ashrrev_i32_e32 v3, 31, v2
	v_lshl_add_u64 v[14:15], v[2:3], 1, v[0:1]
	global_store_dwordx4 v[14:15], v[40:43], off
	s_waitcnt vmcnt(19)
	v_mov_b32_e32 v217, v211
	v_lshlrev_b32_e32 v234, 16, v44
	v_and_b32_e32 v44, 0xffff0000, v44
	v_mul_f32_e32 v238, v44, v44
	v_lshlrev_b32_e32 v235, 16, v45
	v_fmac_f32_e32 v238, v234, v234
	v_and_b32_e32 v45, 0xffff0000, v45
	v_fmac_f32_e32 v238, v235, v235
	v_lshlrev_b32_e32 v236, 16, v46
	v_fmac_f32_e32 v238, v45, v45
	v_and_b32_e32 v46, 0xffff0000, v46
	v_fmac_f32_e32 v238, v236, v236
	v_lshlrev_b32_e32 v237, 16, v47
	v_fmac_f32_e32 v238, v46, v46
	v_and_b32_e32 v47, 0xffff0000, v47
	v_fmac_f32_e32 v238, v237, v237
	v_fmac_f32_e32 v238, v47, v47
	ds_bpermute_b32 v239, v204, v238
	s_waitcnt lgkmcnt(0)
	v_add_f32_e32 v238, v238, v239
	ds_bpermute_b32 v239, v205, v238
	s_waitcnt lgkmcnt(0)
	v_add_f32_e32 v238, v238, v239
	ds_bpermute_b32 v239, v214, v238
	s_waitcnt lgkmcnt(0)
	v_add_f32_e32 v238, v238, v239
	ds_bpermute_b32 v239, v215, v238
	s_waitcnt lgkmcnt(0)
	v_add_f32_e32 v238, v238, v239
	v_fmamk_f32 v238, v238, 0x3c000000, v208
	v_mul_f32_e32 v239, 0x4f800000, v238
	v_cmp_gt_f32_e32 vcc, s33, v238
	s_nop 1
	v_cndmask_b32_e32 v238, v238, v239, vcc
	v_sqrt_f32_e32 v239, v238
	s_nop 0
	v_add_u32_e32 v240, -1, v239
	v_add_u32_e32 v241, 1, v239
	v_fma_f32 v242, -v240, v239, v238
	v_fma_f32 v243, -v241, v239, v238
	v_cmp_ge_f32_e64 s[0:1], 0, v242
	s_nop 1
	v_cndmask_b32_e64 v239, v239, v240, s[0:1]
	v_cmp_lt_f32_e64 s[0:1], 0, v243
	s_nop 1
	v_cndmask_b32_e64 v239, v239, v241, s[0:1]
	v_mul_f32_e32 v240, 0x37800000, v239
	v_cndmask_b32_e32 v239, v239, v240, vcc
	v_cmp_class_f32_e32 vcc, v238, v209
	s_nop 1
	v_cndmask_b32_e32 v238, v239, v238, vcc
	v_div_scale_f32 v239, s[0:1], v238, v238, 1.0
	v_rcp_f32_e32 v241, v239
	v_div_scale_f32 v240, vcc, 1.0, v238, 1.0
	v_fma_f32 v242, -v239, v241, 1.0
	v_fmac_f32_e32 v241, v242, v241
	v_mul_f32_e32 v242, v240, v241
	v_fma_f32 v243, -v239, v242, v240
	v_fmac_f32_e32 v242, v243, v241
	v_fma_f32 v239, -v239, v242, v240
	v_div_fmas_f32 v239, v239, v241, v242
	v_div_fixup_f32 v238, v239, v238, 1.0
	v_mul_f32_e32 v217, v217, v238
	v_mul_f32_e32 v44, v217, v44
	v_mul_f32_e32 v45, v217, v45
	v_mul_f32_e32 v46, v217, v46
	v_mul_f32_e32 v47, v217, v47
	v_mul_f32_e32 v234, v217, v234
	v_mul_f32_e32 v235, v217, v235
	v_mul_f32_e32 v236, v217, v236
	v_mul_f32_e32 v237, v217, v237
	v_mul_f32_e32 v44, v219, v44
	v_mul_f32_e32 v45, v221, v45
	v_mul_f32_e32 v46, v223, v46
	v_mul_f32_e32 v47, v225, v47
	v_mul_f32_e32 v244, v218, v234
	v_mul_f32_e32 v245, v220, v235
	v_mul_f32_e32 v246, v222, v236
	v_mul_f32_e32 v247, v224, v237
	v_cvt_pk_bf16_f32 v44, v244, v44
	v_cvt_pk_bf16_f32 v45, v245, v45
	v_cvt_pk_bf16_f32 v46, v246, v46
	v_cvt_pk_bf16_f32 v47, v247, v47
	v_add_u32_e32 v2, 0x400, v216
	v_ashrrev_i32_e32 v3, 31, v2
	v_lshl_add_u64 v[14:15], v[2:3], 1, v[0:1]
	global_store_dwordx4 v[14:15], v[44:47], off
	s_waitcnt vmcnt(19)
	v_mov_b32_e32 v217, v211
	v_lshlrev_b32_e32 v234, 16, v48
	v_and_b32_e32 v48, 0xffff0000, v48
	v_mul_f32_e32 v238, v48, v48
	v_lshlrev_b32_e32 v235, 16, v49
	v_fmac_f32_e32 v238, v234, v234
	v_and_b32_e32 v49, 0xffff0000, v49
	v_fmac_f32_e32 v238, v235, v235
	v_lshlrev_b32_e32 v236, 16, v50
	v_fmac_f32_e32 v238, v49, v49
	v_and_b32_e32 v50, 0xffff0000, v50
	v_fmac_f32_e32 v238, v236, v236
	v_lshlrev_b32_e32 v237, 16, v51
	v_fmac_f32_e32 v238, v50, v50
	v_and_b32_e32 v51, 0xffff0000, v51
	v_fmac_f32_e32 v238, v237, v237
	v_fmac_f32_e32 v238, v51, v51
	ds_bpermute_b32 v239, v204, v238
	s_waitcnt lgkmcnt(0)
	v_add_f32_e32 v238, v238, v239
	ds_bpermute_b32 v239, v205, v238
	s_waitcnt lgkmcnt(0)
	v_add_f32_e32 v238, v238, v239
	ds_bpermute_b32 v239, v214, v238
	s_waitcnt lgkmcnt(0)
; __device__ __forceinline__ unsigned pk2(float lo, float hi) { return pg8::cvt_pk_bf16(lo, hi); }
; __device__ __forceinline__ void idx_unit(bf16* QB, float* SC, int* SEL, const float* qg, const float* kg, int b, int tp, LAS unsigned char* wl, int lane, bool do_norm) {
;     ...
;             const u32x4 w = *(const u32x4*)ptr;
;             float v[8] = {bflo(w.x), bfhi(w.x), bflo(w.y), bfhi(w.y), bflo(w.z), bfhi(w.z), bflo(w.w), bfhi(w.w)};
;             float s = 0.f;
; #pragma unroll
;             for (int e = 0; e < 8; ++e) s += v[e] * v[e];
;             s += __shfl_xor(s, 1); s += __shfl_xor(s, 2); s += __shfl_xor(s, 4); s += __shfl_xor(s, 8);
;             const float rstd = (1.0f / sqrtf(s * (1.f / 128.f) + RMS_EPS)) * ((p < 4) ? C2 : 1.f);
;             const float* gp = ((p < 4) ? qg : kg) + 8 * li;
;             const f32x4 g0 = *(const f32x4*)gp, g1 = *(const f32x4*)(gp + 4);
;             u32x4 o; o.x = pk2(v[0] * rstd * g0.x, v[1] * rstd * g0.y); o.y = pk2(v[2] * rstd * g0.z, v[3] * rstd * g0.w);
;             o.z = pk2(v[4] * rstd * g1.x, v[5] * rstd * g1.y); o.w = pk2(v[6] * rstd * g1.z, v[7] * rstd * g1.w);
;             *(u32x4*)ptr = o;
;         }
	v_add_f32_e32 v238, v238, v239
	ds_bpermute_b32 v239, v215, v238
	s_waitcnt lgkmcnt(0)
	v_add_f32_e32 v238, v238, v239
	v_fmamk_f32 v238, v238, 0x3c000000, v208
	v_mul_f32_e32 v239, 0x4f800000, v238
	v_cmp_gt_f32_e32 vcc, s33, v238
	s_nop 1
	v_cndmask_b32_e32 v238, v238, v239, vcc
	v_sqrt_f32_e32 v239, v238
	s_nop 0
	v_add_u32_e32 v240, -1, v239
	v_add_u32_e32 v241, 1, v239
	v_fma_f32 v242, -v240, v239, v238
	v_fma_f32 v243, -v241, v239, v238
	v_cmp_ge_f32_e64 s[0:1], 0, v242
	s_nop 1
	v_cndmask_b32_e64 v239, v239, v240, s[0:1]
	v_cmp_lt_f32_e64 s[0:1], 0, v243
	s_nop 1
	v_cndmask_b32_e64 v239, v239, v241, s[0:1]
	v_mul_f32_e32 v240, 0x37800000, v239
	v_cndmask_b32_e32 v239, v239, v240, vcc
	v_cmp_class_f32_e32 vcc, v238, v209
	s_nop 1
	v_cndmask_b32_e32 v238, v239, v238, vcc
	v_div_scale_f32 v239, s[0:1], v238, v238, 1.0
	v_rcp_f32_e32 v241, v239
	v_div_scale_f32 v240, vcc, 1.0, v238, 1.0
	v_fma_f32 v242, -v239, v241, 1.0
	v_fmac_f32_e32 v241, v242, v241
	v_mul_f32_e32 v242, v240, v241
	v_fma_f32 v243, -v239, v242, v240
	v_fmac_f32_e32 v242, v243, v241
	v_fma_f32 v239, -v239, v242, v240
	v_div_fmas_f32 v239, v239, v241, v242
	v_div_fixup_f32 v238, v239, v238, 1.0
	v_mul_f32_e32 v217, v217, v238
	v_mul_f32_e32 v48, v217, v48
	v_mul_f32_e32 v49, v217, v49
	v_mul_f32_e32 v50, v217, v50
	v_mul_f32_e32 v51, v217, v51
	v_mul_f32_e32 v234, v217, v234
	v_mul_f32_e32 v235, v217, v235
	v_mul_f32_e32 v236, v217, v236
	v_mul_f32_e32 v237, v217, v237
	v_mul_f32_e32 v48, v219, v48
	v_mul_f32_e32 v49, v221, v49
	v_mul_f32_e32 v50, v223, v50
	v_mul_f32_e32 v51, v225, v51
	v_mul_f32_e32 v244, v218, v234
	v_mul_f32_e32 v245, v220, v235
	v_mul_f32_e32 v246, v222, v236
	v_mul_f32_e32 v247, v224, v237
	v_cvt_pk_bf16_f32 v48, v244, v48
	v_cvt_pk_bf16_f32 v49, v245, v49
	v_cvt_pk_bf16_f32 v50, v246, v50
	v_cvt_pk_bf16_f32 v51, v247, v51
	v_add_u32_e32 v2, 0x600, v216
	v_ashrrev_i32_e32 v3, 31, v2
	v_lshl_add_u64 v[14:15], v[2:3], 1, v[0:1]
	global_store_dwordx4 v[14:15], v[48:51], off
	s_waitcnt vmcnt(19)
	v_mov_b32_e32 v217, 1.0
	v_lshlrev_b32_e32 v234, 16, v52
	v_and_b32_e32 v52, 0xffff0000, v52
	v_mul_f32_e32 v238, v52, v52
	v_lshlrev_b32_e32 v235, 16, v53
	v_fmac_f32_e32 v238, v234, v234
	v_and_b32_e32 v53, 0xffff0000, v53
	v_fmac_f32_e32 v238, v235, v235
	v_lshlrev_b32_e32 v236, 16, v54
	v_fmac_f32_e32 v238, v53, v53
	v_and_b32_e32 v54, 0xffff0000, v54
	v_fmac_f32_e32 v238, v236, v236
	v_lshlrev_b32_e32 v237, 16, v55
	v_fmac_f32_e32 v238, v54, v54
	v_and_b32_e32 v55, 0xffff0000, v55
	v_fmac_f32_e32 v238, v237, v237
	v_fmac_f32_e32 v238, v55, v55
	ds_bpermute_b32 v239, v204, v238
	s_waitcnt lgkmcnt(0)
	v_add_f32_e32 v238, v238, v239
	ds_bpermute_b32 v239, v205, v238
	s_waitcnt lgkmcnt(0)
	v_add_f32_e32 v238, v238, v239
	ds_bpermute_b32 v239, v214, v238
	s_waitcnt lgkmcnt(0)
	v_add_f32_e32 v238, v238, v239
	ds_bpermute_b32 v239, v215, v238
	s_waitcnt lgkmcnt(0)
	v_add_f32_e32 v238, v238, v239
	v_fmamk_f32 v238, v238, 0x3c000000, v208
	v_mul_f32_e32 v239, 0x4f800000, v238
	v_cmp_gt_f32_e32 vcc, s33, v238
	s_nop 1
	v_cndmask_b32_e32 v238, v238, v239, vcc
	v_sqrt_f32_e32 v239, v238
	s_nop 0
	v_add_u32_e32 v240, -1, v239
	v_add_u32_e32 v241, 1, v239
	v_fma_f32 v242, -v240, v239, v238
	v_fma_f32 v243, -v241, v239, v238
	v_cmp_ge_f32_e64 s[0:1], 0, v242
	s_nop 1
	v_cndmask_b32_e64 v239, v239, v240, s[0:1]
	v_cmp_lt_f32_e64 s[0:1], 0, v243
	s_nop 1
	v_cndmask_b32_e64 v239, v239, v241, s[0:1]
	v_mul_f32_e32 v240, 0x37800000, v239
	v_cndmask_b32_e32 v239, v239, v240, vcc
	v_cmp_class_f32_e32 vcc, v238, v209
	s_nop 1
	v_cndmask_b32_e32 v238, v239, v238, vcc
	v_div_scale_f32 v239, s[0:1], v238, v238, 1.0
	v_rcp_f32_e32 v241, v239
	v_div_scale_f32 v240, vcc, 1.0, v238, 1.0
	v_fma_f32 v242, -v239, v241, 1.0
	v_fmac_f32_e32 v241, v242, v241
	v_mul_f32_e32 v242, v240, v241
	v_fma_f32 v243, -v239, v242, v240
	v_fmac_f32_e32 v242, v243, v241
	v_fma_f32 v239, -v239, v242, v240
	v_div_fmas_f32 v239, v239, v241, v242
	v_div_fixup_f32 v238, v239, v238, 1.0
	v_mul_f32_e32 v217, v217, v238
	v_mul_f32_e32 v52, v217, v52
	v_mul_f32_e32 v53, v217, v53
	v_mul_f32_e32 v54, v217, v54
	v_mul_f32_e32 v55, v217, v55
	v_mul_f32_e32 v234, v217, v234
	v_mul_f32_e32 v235, v217, v235
	v_mul_f32_e32 v236, v217, v236
	v_mul_f32_e32 v237, v217, v237
	v_mul_f32_e32 v52, v227, v52
	v_mul_f32_e32 v53, v229, v53
	v_mul_f32_e32 v54, v231, v54
	v_mul_f32_e32 v55, v233, v55
	v_mul_f32_e32 v244, v226, v234
	v_mul_f32_e32 v245, v228, v235
	v_mul_f32_e32 v246, v230, v236
	v_mul_f32_e32 v247, v232, v237
	v_cvt_pk_bf16_f32 v52, v244, v52
	v_cvt_pk_bf16_f32 v53, v245, v53
	v_cvt_pk_bf16_f32 v54, v246, v54
	v_cvt_pk_bf16_f32 v55, v247, v55
	v_add_u32_e32 v2, 0x800, v216
	v_ashrrev_i32_e32 v3, 31, v2
	v_lshl_add_u64 v[14:15], v[2:3], 1, v[0:1]
	global_store_dwordx4 v[14:15], v[52:55], off
	s_add_u32 s0, s2, 2
	s_addc_u32 s1, s79, 0
	s_mul_i32 s4, s1, 0x2200
	v_mad_u64_u32 v[0:1], s[0:1], s0, v212, v[118:119]
	v_add_u32_e32 v1, s4, v1
	s_waitcnt vmcnt(19)
	v_mov_b32_e32 v217, v211
	v_lshlrev_b32_e32 v234, 16, v56
	v_and_b32_e32 v56, 0xffff0000, v56
	v_mul_f32_e32 v238, v56, v56
	v_lshlrev_b32_e32 v235, 16, v57
	v_fmac_f32_e32 v238, v234, v234
	v_and_b32_e32 v57, 0xffff0000, v57
	v_fmac_f32_e32 v238, v235, v235
	v_lshlrev_b32_e32 v236, 16, v58
	v_fmac_f32_e32 v238, v57, v57
	v_and_b32_e32 v58, 0xffff0000, v58
	v_fmac_f32_e32 v238, v236, v236
	v_lshlrev_b32_e32 v237, 16, v59
	v_fmac_f32_e32 v238, v58, v58
	v_and_b32_e32 v59, 0xffff0000, v59
	v_fmac_f32_e32 v238, v237, v237
	v_fmac_f32_e32 v238, v59, v59
	ds_bpermute_b32 v239, v204, v238
	s_waitcnt lgkmcnt(0)
	v_add_f32_e32 v238, v238, v239
	ds_bpermute_b32 v239, v205, v238
	s_waitcnt lgkmcnt(0)
; __device__ __forceinline__ unsigned pk2(float lo, float hi) { return pg8::cvt_pk_bf16(lo, hi); }
; __device__ __forceinline__ void idx_unit(bf16* QB, float* SC, int* SEL, const float* qg, const float* kg, int b, int tp, LAS unsigned char* wl, int lane, bool do_norm) {
;     ...
;             const u32x4 w = *(const u32x4*)ptr;
;             float v[8] = {bflo(w.x), bfhi(w.x), bflo(w.y), bfhi(w.y), bflo(w.z), bfhi(w.z), bflo(w.w), bfhi(w.w)};
;             float s = 0.f;
; #pragma unroll
;             for (int e = 0; e < 8; ++e) s += v[e] * v[e];
;             s += __shfl_xor(s, 1); s += __shfl_xor(s, 2); s += __shfl_xor(s, 4); s += __shfl_xor(s, 8);
;             const float rstd = (1.0f / sqrtf(s * (1.f / 128.f) + RMS_EPS)) * ((p < 4) ? C2 : 1.f);
;             const float* gp = ((p < 4) ? qg : kg) + 8 * li;
;             const f32x4 g0 = *(const f32x4*)gp, g1 = *(const f32x4*)(gp + 4);
;             u32x4 o; o.x = pk2(v[0] * rstd * g0.x, v[1] * rstd * g0.y); o.y = pk2(v[2] * rstd * g0.z, v[3] * rstd * g0.w);
;             o.z = pk2(v[4] * rstd * g1.x, v[5] * rstd * g1.y); o.w = pk2(v[6] * rstd * g1.z, v[7] * rstd * g1.w);
;             *(u32x4*)ptr = o;
;         }
	v_add_f32_e32 v238, v238, v239
	ds_bpermute_b32 v239, v214, v238
	s_waitcnt lgkmcnt(0)
	v_add_f32_e32 v238, v238, v239
	ds_bpermute_b32 v239, v215, v238
	s_waitcnt lgkmcnt(0)
	v_add_f32_e32 v238, v238, v239
	v_fmamk_f32 v238, v238, 0x3c000000, v208
	v_mul_f32_e32 v239, 0x4f800000, v238
	v_cmp_gt_f32_e32 vcc, s33, v238
	s_nop 1
	v_cndmask_b32_e32 v238, v238, v239, vcc
	v_sqrt_f32_e32 v239, v238
	s_nop 0
	v_add_u32_e32 v240, -1, v239
	v_add_u32_e32 v241, 1, v239
	v_fma_f32 v242, -v240, v239, v238
	v_fma_f32 v243, -v241, v239, v238
	v_cmp_ge_f32_e64 s[0:1], 0, v242
	s_nop 1
	v_cndmask_b32_e64 v239, v239, v240, s[0:1]
	v_cmp_lt_f32_e64 s[0:1], 0, v243
	s_nop 1
	v_cndmask_b32_e64 v239, v239, v241, s[0:1]
	v_mul_f32_e32 v240, 0x37800000, v239
	v_cndmask_b32_e32 v239, v239, v240, vcc
	v_cmp_class_f32_e32 vcc, v238, v209
	s_nop 1
	v_cndmask_b32_e32 v238, v239, v238, vcc
	v_div_scale_f32 v239, s[0:1], v238, v238, 1.0
	v_rcp_f32_e32 v241, v239
	v_div_scale_f32 v240, vcc, 1.0, v238, 1.0
	v_fma_f32 v242, -v239, v241, 1.0
	v_fmac_f32_e32 v241, v242, v241
	v_mul_f32_e32 v242, v240, v241
	v_fma_f32 v243, -v239, v242, v240
	v_fmac_f32_e32 v242, v243, v241
	v_fma_f32 v239, -v239, v242, v240
	v_div_fmas_f32 v239, v239, v241, v242
	v_div_fixup_f32 v238, v239, v238, 1.0
	v_mul_f32_e32 v217, v217, v238
	v_mul_f32_e32 v56, v217, v56
	v_mul_f32_e32 v57, v217, v57
	v_mul_f32_e32 v58, v217, v58
	v_mul_f32_e32 v59, v217, v59
	v_mul_f32_e32 v234, v217, v234
	v_mul_f32_e32 v235, v217, v235
	v_mul_f32_e32 v236, v217, v236
	v_mul_f32_e32 v237, v217, v237
	v_mul_f32_e32 v56, v219, v56
	v_mul_f32_e32 v57, v221, v57
	v_mul_f32_e32 v58, v223, v58
	v_mul_f32_e32 v59, v225, v59
	v_mul_f32_e32 v244, v218, v234
	v_mul_f32_e32 v245, v220, v235
	v_mul_f32_e32 v246, v222, v236
	v_mul_f32_e32 v247, v224, v237
	v_cvt_pk_bf16_f32 v56, v244, v56
	v_cvt_pk_bf16_f32 v57, v245, v57
	v_cvt_pk_bf16_f32 v58, v246, v58
	v_cvt_pk_bf16_f32 v59, v247, v59
	v_mov_b32_e32 v2, v216
	v_ashrrev_i32_e32 v3, 31, v2
	v_lshl_add_u64 v[14:15], v[2:3], 1, v[0:1]
	global_store_dwordx4 v[14:15], v[56:59], off
	s_waitcnt vmcnt(19)
	v_mov_b32_e32 v217, v211
	v_lshlrev_b32_e32 v234, 16, v60
	v_and_b32_e32 v60, 0xffff0000, v60
	v_mul_f32_e32 v238, v60, v60
	v_lshlrev_b32_e32 v235, 16, v61
	v_fmac_f32_e32 v238, v234, v234
	v_and_b32_e32 v61, 0xffff0000, v61
	v_fmac_f32_e32 v238, v235, v235
	v_lshlrev_b32_e32 v236, 16, v62
	v_fmac_f32_e32 v238, v61, v61
	v_and_b32_e32 v62, 0xffff0000, v62
	v_fmac_f32_e32 v238, v236, v236
	v_lshlrev_b32_e32 v237, 16, v63
	v_fmac_f32_e32 v238, v62, v62
	v_and_b32_e32 v63, 0xffff0000, v63
	v_fmac_f32_e32 v238, v237, v237
	v_fmac_f32_e32 v238, v63, v63
	ds_bpermute_b32 v239, v204, v238
	s_waitcnt lgkmcnt(0)
	v_add_f32_e32 v238, v238, v239
	ds_bpermute_b32 v239, v205, v238
	s_waitcnt lgkmcnt(0)
	v_add_f32_e32 v238, v238, v239
	ds_bpermute_b32 v239, v214, v238
	s_waitcnt lgkmcnt(0)
	v_add_f32_e32 v238, v238, v239
	ds_bpermute_b32 v239, v215, v238
	s_waitcnt lgkmcnt(0)
	v_add_f32_e32 v238, v238, v239
	v_fmamk_f32 v238, v238, 0x3c000000, v208
	v_mul_f32_e32 v239, 0x4f800000, v238
	v_cmp_gt_f32_e32 vcc, s33, v238
	s_nop 1
	v_cndmask_b32_e32 v238, v238, v239, vcc
	v_sqrt_f32_e32 v239, v238
	s_nop 0
	v_add_u32_e32 v240, -1, v239
	v_add_u32_e32 v241, 1, v239
	v_fma_f32 v242, -v240, v239, v238
	v_fma_f32 v243, -v241, v239, v238
	v_cmp_ge_f32_e64 s[0:1], 0, v242
	s_nop 1
	v_cndmask_b32_e64 v239, v239, v240, s[0:1]
	v_cmp_lt_f32_e64 s[0:1], 0, v243
	s_nop 1
	v_cndmask_b32_e64 v239, v239, v241, s[0:1]
	v_mul_f32_e32 v240, 0x37800000, v239
	v_cndmask_b32_e32 v239, v239, v240, vcc
	v_cmp_class_f32_e32 vcc, v238, v209
	s_nop 1
	v_cndmask_b32_e32 v238, v239, v238, vcc
	v_div_scale_f32 v239, s[0:1], v238, v238, 1.0
	v_rcp_f32_e32 v241, v239
	v_div_scale_f32 v240, vcc, 1.0, v238, 1.0
	v_fma_f32 v242, -v239, v241, 1.0
	v_fmac_f32_e32 v241, v242, v241
	v_mul_f32_e32 v242, v240, v241
	v_fma_f32 v243, -v239, v242, v240
	v_fmac_f32_e32 v242, v243, v241
	v_fma_f32 v239, -v239, v242, v240
	v_div_fmas_f32 v239, v239, v241, v242
	v_div_fixup_f32 v238, v239, v238, 1.0
	v_mul_f32_e32 v217, v217, v238
	v_mul_f32_e32 v60, v217, v60
	v_mul_f32_e32 v61, v217, v61
	v_mul_f32_e32 v62, v217, v62
	v_mul_f32_e32 v63, v217, v63
	v_mul_f32_e32 v234, v217, v234
	v_mul_f32_e32 v235, v217, v235
	v_mul_f32_e32 v236, v217, v236
	v_mul_f32_e32 v237, v217, v237
	v_mul_f32_e32 v60, v219, v60
	v_mul_f32_e32 v61, v221, v61
	v_mul_f32_e32 v62, v223, v62
	v_mul_f32_e32 v63, v225, v63
	v_mul_f32_e32 v244, v218, v234
	v_mul_f32_e32 v245, v220, v235
	v_mul_f32_e32 v246, v222, v236
	v_mul_f32_e32 v247, v224, v237
	v_cvt_pk_bf16_f32 v60, v244, v60
	v_cvt_pk_bf16_f32 v61, v245, v61
	v_cvt_pk_bf16_f32 v62, v246, v62
	v_cvt_pk_bf16_f32 v63, v247, v63
	v_add_u32_e32 v2, 0x200, v216
	v_ashrrev_i32_e32 v3, 31, v2
	v_lshl_add_u64 v[14:15], v[2:3], 1, v[0:1]
	global_store_dwordx4 v[14:15], v[60:63], off
	s_waitcnt vmcnt(19)
	v_mov_b32_e32 v217, v211
	v_lshlrev_b32_e32 v234, 16, v64
	v_and_b32_e32 v64, 0xffff0000, v64
	v_mul_f32_e32 v238, v64, v64
	v_lshlrev_b32_e32 v235, 16, v65
	v_fmac_f32_e32 v238, v234, v234
	v_and_b32_e32 v65, 0xffff0000, v65
	v_fmac_f32_e32 v238, v235, v235
	v_lshlrev_b32_e32 v236, 16, v66
	v_fmac_f32_e32 v238, v65, v65
	v_and_b32_e32 v66, 0xffff0000, v66
	v_fmac_f32_e32 v238, v236, v236
	v_lshlrev_b32_e32 v237, 16, v67
	v_fmac_f32_e32 v238, v66, v66
	v_and_b32_e32 v67, 0xffff0000, v67
	v_fmac_f32_e32 v238, v237, v237
	v_fmac_f32_e32 v238, v67, v67
	ds_bpermute_b32 v239, v204, v238
	s_waitcnt lgkmcnt(0)
	v_add_f32_e32 v238, v238, v239
	ds_bpermute_b32 v239, v205, v238
	s_waitcnt lgkmcnt(0)
; __device__ __forceinline__ unsigned pk2(float lo, float hi) { return pg8::cvt_pk_bf16(lo, hi); }
; __device__ __forceinline__ void idx_unit(bf16* QB, float* SC, int* SEL, const float* qg, const float* kg, int b, int tp, LAS unsigned char* wl, int lane, bool do_norm) {
;     ...
;             const u32x4 w = *(const u32x4*)ptr;
;             float v[8] = {bflo(w.x), bfhi(w.x), bflo(w.y), bfhi(w.y), bflo(w.z), bfhi(w.z), bflo(w.w), bfhi(w.w)};
;             float s = 0.f;
; #pragma unroll
;             for (int e = 0; e < 8; ++e) s += v[e] * v[e];
;             s += __shfl_xor(s, 1); s += __shfl_xor(s, 2); s += __shfl_xor(s, 4); s += __shfl_xor(s, 8);
;             const float rstd = (1.0f / sqrtf(s * (1.f / 128.f) + RMS_EPS)) * ((p < 4) ? C2 : 1.f);
;             const float* gp = ((p < 4) ? qg : kg) + 8 * li;
;             const f32x4 g0 = *(const f32x4*)gp, g1 = *(const f32x4*)(gp + 4);
;             u32x4 o; o.x = pk2(v[0] * rstd * g0.x, v[1] * rstd * g0.y); o.y = pk2(v[2] * rstd * g0.z, v[3] * rstd * g0.w);
;             o.z = pk2(v[4] * rstd * g1.x, v[5] * rstd * g1.y); o.w = pk2(v[6] * rstd * g1.z, v[7] * rstd * g1.w);
;             *(u32x4*)ptr = o;
;         }
	v_add_f32_e32 v238, v238, v239
	ds_bpermute_b32 v239, v214, v238
	s_waitcnt lgkmcnt(0)
	v_add_f32_e32 v238, v238, v239
	ds_bpermute_b32 v239, v215, v238
	s_waitcnt lgkmcnt(0)
	v_add_f32_e32 v238, v238, v239
	v_fmamk_f32 v238, v238, 0x3c000000, v208
	v_mul_f32_e32 v239, 0x4f800000, v238
	v_cmp_gt_f32_e32 vcc, s33, v238
	s_nop 1
	v_cndmask_b32_e32 v238, v238, v239, vcc
	v_sqrt_f32_e32 v239, v238
	s_nop 0
	v_add_u32_e32 v240, -1, v239
	v_add_u32_e32 v241, 1, v239
	v_fma_f32 v242, -v240, v239, v238
	v_fma_f32 v243, -v241, v239, v238
	v_cmp_ge_f32_e64 s[0:1], 0, v242
	s_nop 1
	v_cndmask_b32_e64 v239, v239, v240, s[0:1]
	v_cmp_lt_f32_e64 s[0:1], 0, v243
	s_nop 1
	v_cndmask_b32_e64 v239, v239, v241, s[0:1]
	v_mul_f32_e32 v240, 0x37800000, v239
	v_cndmask_b32_e32 v239, v239, v240, vcc
	v_cmp_class_f32_e32 vcc, v238, v209
	s_nop 1
	v_cndmask_b32_e32 v238, v239, v238, vcc
	v_div_scale_f32 v239, s[0:1], v238, v238, 1.0
	v_rcp_f32_e32 v241, v239
	v_div_scale_f32 v240, vcc, 1.0, v238, 1.0
	v_fma_f32 v242, -v239, v241, 1.0
	v_fmac_f32_e32 v241, v242, v241
	v_mul_f32_e32 v242, v240, v241
	v_fma_f32 v243, -v239, v242, v240
	v_fmac_f32_e32 v242, v243, v241
	v_fma_f32 v239, -v239, v242, v240
	v_div_fmas_f32 v239, v239, v241, v242
	v_div_fixup_f32 v238, v239, v238, 1.0
	v_mul_f32_e32 v217, v217, v238
	v_mul_f32_e32 v64, v217, v64
	v_mul_f32_e32 v65, v217, v65
	v_mul_f32_e32 v66, v217, v66
	v_mul_f32_e32 v67, v217, v67
	v_mul_f32_e32 v234, v217, v234
	v_mul_f32_e32 v235, v217, v235
	v_mul_f32_e32 v236, v217, v236
	v_mul_f32_e32 v237, v217, v237
	v_mul_f32_e32 v64, v219, v64
	v_mul_f32_e32 v65, v221, v65
	v_mul_f32_e32 v66, v223, v66
	v_mul_f32_e32 v67, v225, v67
	v_mul_f32_e32 v244, v218, v234
	v_mul_f32_e32 v245, v220, v235
	v_mul_f32_e32 v246, v222, v236
	v_mul_f32_e32 v247, v224, v237
	v_cvt_pk_bf16_f32 v64, v244, v64
	v_cvt_pk_bf16_f32 v65, v245, v65
	v_cvt_pk_bf16_f32 v66, v246, v66
	v_cvt_pk_bf16_f32 v67, v247, v67
	v_add_u32_e32 v2, 0x400, v216
	v_ashrrev_i32_e32 v3, 31, v2
	v_lshl_add_u64 v[14:15], v[2:3], 1, v[0:1]
	global_store_dwordx4 v[14:15], v[64:67], off
	s_waitcnt vmcnt(19)
	v_mov_b32_e32 v217, v211
	v_lshlrev_b32_e32 v234, 16, v68
	v_and_b32_e32 v68, 0xffff0000, v68
	v_mul_f32_e32 v238, v68, v68
	v_lshlrev_b32_e32 v235, 16, v69
	v_fmac_f32_e32 v238, v234, v234
	v_and_b32_e32 v69, 0xffff0000, v69
	v_fmac_f32_e32 v238, v235, v235
	v_lshlrev_b32_e32 v236, 16, v70
	v_fmac_f32_e32 v238, v69, v69
	v_and_b32_e32 v70, 0xffff0000, v70
	v_fmac_f32_e32 v238, v236, v236
	v_lshlrev_b32_e32 v237, 16, v71
	v_fmac_f32_e32 v238, v70, v70
	v_and_b32_e32 v71, 0xffff0000, v71
	v_fmac_f32_e32 v238, v237, v237
	v_fmac_f32_e32 v238, v71, v71
	ds_bpermute_b32 v239, v204, v238
	s_waitcnt lgkmcnt(0)
	v_add_f32_e32 v238, v238, v239
	ds_bpermute_b32 v239, v205, v238
	s_waitcnt lgkmcnt(0)
	v_add_f32_e32 v238, v238, v239
	ds_bpermute_b32 v239, v214, v238
	s_waitcnt lgkmcnt(0)
	v_add_f32_e32 v238, v238, v239
	ds_bpermute_b32 v239, v215, v238
	s_waitcnt lgkmcnt(0)
	v_add_f32_e32 v238, v238, v239
	v_fmamk_f32 v238, v238, 0x3c000000, v208
	v_mul_f32_e32 v239, 0x4f800000, v238
	v_cmp_gt_f32_e32 vcc, s33, v238
	s_nop 1
	v_cndmask_b32_e32 v238, v238, v239, vcc
	v_sqrt_f32_e32 v239, v238
	s_nop 0
	v_add_u32_e32 v240, -1, v239
	v_add_u32_e32 v241, 1, v239
	v_fma_f32 v242, -v240, v239, v238
	v_fma_f32 v243, -v241, v239, v238
	v_cmp_ge_f32_e64 s[0:1], 0, v242
	s_nop 1
	v_cndmask_b32_e64 v239, v239, v240, s[0:1]
	v_cmp_lt_f32_e64 s[0:1], 0, v243
	s_nop 1
	v_cndmask_b32_e64 v239, v239, v241, s[0:1]
	v_mul_f32_e32 v240, 0x37800000, v239
	v_cndmask_b32_e32 v239, v239, v240, vcc
	v_cmp_class_f32_e32 vcc, v238, v209
	s_nop 1
	v_cndmask_b32_e32 v238, v239, v238, vcc
	v_div_scale_f32 v239, s[0:1], v238, v238, 1.0
	v_rcp_f32_e32 v241, v239
	v_div_scale_f32 v240, vcc, 1.0, v238, 1.0
	v_fma_f32 v242, -v239, v241, 1.0
	v_fmac_f32_e32 v241, v242, v241
	v_mul_f32_e32 v242, v240, v241
	v_fma_f32 v243, -v239, v242, v240
	v_fmac_f32_e32 v242, v243, v241
	v_fma_f32 v239, -v239, v242, v240
	v_div_fmas_f32 v239, v239, v241, v242
	v_div_fixup_f32 v238, v239, v238, 1.0
	v_mul_f32_e32 v217, v217, v238
	v_mul_f32_e32 v68, v217, v68
	v_mul_f32_e32 v69, v217, v69
	v_mul_f32_e32 v70, v217, v70
	v_mul_f32_e32 v71, v217, v71
	v_mul_f32_e32 v234, v217, v234
	v_mul_f32_e32 v235, v217, v235
	v_mul_f32_e32 v236, v217, v236
	v_mul_f32_e32 v237, v217, v237
	v_mul_f32_e32 v68, v219, v68
	v_mul_f32_e32 v69, v221, v69
	v_mul_f32_e32 v70, v223, v70
	v_mul_f32_e32 v71, v225, v71
	v_mul_f32_e32 v244, v218, v234
	v_mul_f32_e32 v245, v220, v235
	v_mul_f32_e32 v246, v222, v236
	v_mul_f32_e32 v247, v224, v237
	v_cvt_pk_bf16_f32 v68, v244, v68
	v_cvt_pk_bf16_f32 v69, v245, v69
	v_cvt_pk_bf16_f32 v70, v246, v70
	v_cvt_pk_bf16_f32 v71, v247, v71
	v_add_u32_e32 v2, 0x600, v216
	v_ashrrev_i32_e32 v3, 31, v2
	v_lshl_add_u64 v[14:15], v[2:3], 1, v[0:1]
	global_store_dwordx4 v[14:15], v[68:71], off
	s_waitcnt vmcnt(19)
	v_mov_b32_e32 v217, 1.0
	v_lshlrev_b32_e32 v234, 16, v72
	v_and_b32_e32 v72, 0xffff0000, v72
	v_mul_f32_e32 v238, v72, v72
	v_lshlrev_b32_e32 v235, 16, v73
	v_fmac_f32_e32 v238, v234, v234
	v_and_b32_e32 v73, 0xffff0000, v73
	v_fmac_f32_e32 v238, v235, v235
	v_lshlrev_b32_e32 v236, 16, v74
	v_fmac_f32_e32 v238, v73, v73
	v_and_b32_e32 v74, 0xffff0000, v74
	v_fmac_f32_e32 v238, v236, v236
	v_lshlrev_b32_e32 v237, 16, v75
	v_fmac_f32_e32 v238, v74, v74
	v_and_b32_e32 v75, 0xffff0000, v75
	v_fmac_f32_e32 v238, v237, v237
	v_fmac_f32_e32 v238, v75, v75
	ds_bpermute_b32 v239, v204, v238
	s_waitcnt lgkmcnt(0)
	v_add_f32_e32 v238, v238, v239
	ds_bpermute_b32 v239, v205, v238
	s_waitcnt lgkmcnt(0)
; __device__ __forceinline__ unsigned pk2(float lo, float hi) { return pg8::cvt_pk_bf16(lo, hi); }
; __device__ __forceinline__ void idx_unit(bf16* QB, float* SC, int* SEL, const float* qg, const float* kg, int b, int tp, LAS unsigned char* wl, int lane, bool do_norm) {
;     ...
;             const u32x4 w = *(const u32x4*)ptr;
;             float v[8] = {bflo(w.x), bfhi(w.x), bflo(w.y), bfhi(w.y), bflo(w.z), bfhi(w.z), bflo(w.w), bfhi(w.w)};
;             float s = 0.f;
; #pragma unroll
;             for (int e = 0; e < 8; ++e) s += v[e] * v[e];
;             s += __shfl_xor(s, 1); s += __shfl_xor(s, 2); s += __shfl_xor(s, 4); s += __shfl_xor(s, 8);
;             const float rstd = (1.0f / sqrtf(s * (1.f / 128.f) + RMS_EPS)) * ((p < 4) ? C2 : 1.f);
;             const float* gp = ((p < 4) ? qg : kg) + 8 * li;
;             const f32x4 g0 = *(const f32x4*)gp, g1 = *(const f32x4*)(gp + 4);
;             u32x4 o; o.x = pk2(v[0] * rstd * g0.x, v[1] * rstd * g0.y); o.y = pk2(v[2] * rstd * g0.z, v[3] * rstd * g0.w);
;             o.z = pk2(v[4] * rstd * g1.x, v[5] * rstd * g1.y); o.w = pk2(v[6] * rstd * g1.z, v[7] * rstd * g1.w);
;             *(u32x4*)ptr = o;
;         }
	v_add_f32_e32 v238, v238, v239
	ds_bpermute_b32 v239, v214, v238
	s_waitcnt lgkmcnt(0)
	v_add_f32_e32 v238, v238, v239
	ds_bpermute_b32 v239, v215, v238
	s_waitcnt lgkmcnt(0)
	v_add_f32_e32 v238, v238, v239
	v_fmamk_f32 v238, v238, 0x3c000000, v208
	v_mul_f32_e32 v239, 0x4f800000, v238
	v_cmp_gt_f32_e32 vcc, s33, v238
	s_nop 1
	v_cndmask_b32_e32 v238, v238, v239, vcc
	v_sqrt_f32_e32 v239, v238
	s_nop 0
	v_add_u32_e32 v240, -1, v239
	v_add_u32_e32 v241, 1, v239
	v_fma_f32 v242, -v240, v239, v238
	v_fma_f32 v243, -v241, v239, v238
	v_cmp_ge_f32_e64 s[0:1], 0, v242
	s_nop 1
	v_cndmask_b32_e64 v239, v239, v240, s[0:1]
	v_cmp_lt_f32_e64 s[0:1], 0, v243
	s_nop 1
	v_cndmask_b32_e64 v239, v239, v241, s[0:1]
	v_mul_f32_e32 v240, 0x37800000, v239
	v_cndmask_b32_e32 v239, v239, v240, vcc
	v_cmp_class_f32_e32 vcc, v238, v209
	s_nop 1
	v_cndmask_b32_e32 v238, v239, v238, vcc
	v_div_scale_f32 v239, s[0:1], v238, v238, 1.0
	v_rcp_f32_e32 v241, v239
	v_div_scale_f32 v240, vcc, 1.0, v238, 1.0
	v_fma_f32 v242, -v239, v241, 1.0
	v_fmac_f32_e32 v241, v242, v241
	v_mul_f32_e32 v242, v240, v241
	v_fma_f32 v243, -v239, v242, v240
	v_fmac_f32_e32 v242, v243, v241
	v_fma_f32 v239, -v239, v242, v240
	v_div_fmas_f32 v239, v239, v241, v242
	v_div_fixup_f32 v238, v239, v238, 1.0
	v_mul_f32_e32 v217, v217, v238
	v_mul_f32_e32 v72, v217, v72
	v_mul_f32_e32 v73, v217, v73
	v_mul_f32_e32 v74, v217, v74
	v_mul_f32_e32 v75, v217, v75
	v_mul_f32_e32 v234, v217, v234
	v_mul_f32_e32 v235, v217, v235
	v_mul_f32_e32 v236, v217, v236
	v_mul_f32_e32 v237, v217, v237
	v_mul_f32_e32 v72, v227, v72
	v_mul_f32_e32 v73, v229, v73
	v_mul_f32_e32 v74, v231, v74
	v_mul_f32_e32 v75, v233, v75
	v_mul_f32_e32 v244, v226, v234
	v_mul_f32_e32 v245, v228, v235
	v_mul_f32_e32 v246, v230, v236
	v_mul_f32_e32 v247, v232, v237
	v_cvt_pk_bf16_f32 v72, v244, v72
	v_cvt_pk_bf16_f32 v73, v245, v73
	v_cvt_pk_bf16_f32 v74, v246, v74
	v_cvt_pk_bf16_f32 v75, v247, v75
	v_add_u32_e32 v2, 0x800, v216
	v_ashrrev_i32_e32 v3, 31, v2
	v_lshl_add_u64 v[14:15], v[2:3], 1, v[0:1]
	global_store_dwordx4 v[14:15], v[72:75], off
	s_add_u32 s0, s2, 3
	s_addc_u32 s1, s79, 0
	s_mul_i32 s4, s1, 0x2200
	v_mad_u64_u32 v[0:1], s[0:1], s0, v212, v[118:119]
	v_add_u32_e32 v1, s4, v1
	s_waitcnt vmcnt(19)
	v_mov_b32_e32 v217, v211
	v_lshlrev_b32_e32 v234, 16, v76
	v_and_b32_e32 v76, 0xffff0000, v76
	v_mul_f32_e32 v238, v76, v76
	v_lshlrev_b32_e32 v235, 16, v77
	v_fmac_f32_e32 v238, v234, v234
	v_and_b32_e32 v77, 0xffff0000, v77
	v_fmac_f32_e32 v238, v235, v235
	v_lshlrev_b32_e32 v236, 16, v78
	v_fmac_f32_e32 v238, v77, v77
	v_and_b32_e32 v78, 0xffff0000, v78
	v_fmac_f32_e32 v238, v236, v236
	v_lshlrev_b32_e32 v237, 16, v79
	v_fmac_f32_e32 v238, v78, v78
	v_and_b32_e32 v79, 0xffff0000, v79
	v_fmac_f32_e32 v238, v237, v237
	v_fmac_f32_e32 v238, v79, v79
	ds_bpermute_b32 v239, v204, v238
	s_waitcnt lgkmcnt(0)
	v_add_f32_e32 v238, v238, v239
	ds_bpermute_b32 v239, v205, v238
	s_waitcnt lgkmcnt(0)
	v_add_f32_e32 v238, v238, v239
	ds_bpermute_b32 v239, v214, v238
	s_waitcnt lgkmcnt(0)
	v_add_f32_e32 v238, v238, v239
	ds_bpermute_b32 v239, v215, v238
	s_waitcnt lgkmcnt(0)
	v_add_f32_e32 v238, v238, v239
	v_fmamk_f32 v238, v238, 0x3c000000, v208
	v_mul_f32_e32 v239, 0x4f800000, v238
	v_cmp_gt_f32_e32 vcc, s33, v238
	s_nop 1
	v_cndmask_b32_e32 v238, v238, v239, vcc
	v_sqrt_f32_e32 v239, v238
	s_nop 0
	v_add_u32_e32 v240, -1, v239
	v_add_u32_e32 v241, 1, v239
	v_fma_f32 v242, -v240, v239, v238
	v_fma_f32 v243, -v241, v239, v238
	v_cmp_ge_f32_e64 s[0:1], 0, v242
	s_nop 1
	v_cndmask_b32_e64 v239, v239, v240, s[0:1]
	v_cmp_lt_f32_e64 s[0:1], 0, v243
	s_nop 1
	v_cndmask_b32_e64 v239, v239, v241, s[0:1]
	v_mul_f32_e32 v240, 0x37800000, v239
	v_cndmask_b32_e32 v239, v239, v240, vcc
	v_cmp_class_f32_e32 vcc, v238, v209
	s_nop 1
	v_cndmask_b32_e32 v238, v239, v238, vcc
	v_div_scale_f32 v239, s[0:1], v238, v238, 1.0
	v_rcp_f32_e32 v241, v239
	v_div_scale_f32 v240, vcc, 1.0, v238, 1.0
	v_fma_f32 v242, -v239, v241, 1.0
	v_fmac_f32_e32 v241, v242, v241
	v_mul_f32_e32 v242, v240, v241
	v_fma_f32 v243, -v239, v242, v240
	v_fmac_f32_e32 v242, v243, v241
	v_fma_f32 v239, -v239, v242, v240
	v_div_fmas_f32 v239, v239, v241, v242
	v_div_fixup_f32 v238, v239, v238, 1.0
	v_mul_f32_e32 v217, v217, v238
	v_mul_f32_e32 v76, v217, v76
	v_mul_f32_e32 v77, v217, v77
	v_mul_f32_e32 v78, v217, v78
	v_mul_f32_e32 v79, v217, v79
	v_mul_f32_e32 v234, v217, v234
	v_mul_f32_e32 v235, v217, v235
	v_mul_f32_e32 v236, v217, v236
	v_mul_f32_e32 v237, v217, v237
	v_mul_f32_e32 v76, v219, v76
	v_mul_f32_e32 v77, v221, v77
	v_mul_f32_e32 v78, v223, v78
	v_mul_f32_e32 v79, v225, v79
	v_mul_f32_e32 v244, v218, v234
	v_mul_f32_e32 v245, v220, v235
	v_mul_f32_e32 v246, v222, v236
	v_mul_f32_e32 v247, v224, v237
	v_cvt_pk_bf16_f32 v76, v244, v76
	v_cvt_pk_bf16_f32 v77, v245, v77
	v_cvt_pk_bf16_f32 v78, v246, v78
	v_cvt_pk_bf16_f32 v79, v247, v79
	v_mov_b32_e32 v2, v216
	v_ashrrev_i32_e32 v3, 31, v2
	v_lshl_add_u64 v[14:15], v[2:3], 1, v[0:1]
	global_store_dwordx4 v[14:15], v[76:79], off
	s_waitcnt vmcnt(19)
	v_mov_b32_e32 v217, v211
	v_lshlrev_b32_e32 v234, 16, v80
	v_and_b32_e32 v80, 0xffff0000, v80
	v_mul_f32_e32 v238, v80, v80
	v_lshlrev_b32_e32 v235, 16, v81
	v_fmac_f32_e32 v238, v234, v234
	v_and_b32_e32 v81, 0xffff0000, v81
	v_fmac_f32_e32 v238, v235, v235
	v_lshlrev_b32_e32 v236, 16, v82
	v_fmac_f32_e32 v238, v81, v81
	v_and_b32_e32 v82, 0xffff0000, v82
	v_fmac_f32_e32 v238, v236, v236
	v_lshlrev_b32_e32 v237, 16, v83
	v_fmac_f32_e32 v238, v82, v82
	v_and_b32_e32 v83, 0xffff0000, v83
	v_fmac_f32_e32 v238, v237, v237
	v_fmac_f32_e32 v238, v83, v83
	ds_bpermute_b32 v239, v204, v238
	s_waitcnt lgkmcnt(0)
; __device__ __forceinline__ unsigned pk2(float lo, float hi) { return pg8::cvt_pk_bf16(lo, hi); }
; __device__ __forceinline__ void idx_unit(bf16* QB, float* SC, int* SEL, const float* qg, const float* kg, int b, int tp, LAS unsigned char* wl, int lane, bool do_norm) {
;     ...
;             const u32x4 w = *(const u32x4*)ptr;
;             float v[8] = {bflo(w.x), bfhi(w.x), bflo(w.y), bfhi(w.y), bflo(w.z), bfhi(w.z), bflo(w.w), bfhi(w.w)};
;             float s = 0.f;
; #pragma unroll
;             for (int e = 0; e < 8; ++e) s += v[e] * v[e];
;             s += __shfl_xor(s, 1); s += __shfl_xor(s, 2); s += __shfl_xor(s, 4); s += __shfl_xor(s, 8);
;             const float rstd = (1.0f / sqrtf(s * (1.f / 128.f) + RMS_EPS)) * ((p < 4) ? C2 : 1.f);
;             const float* gp = ((p < 4) ? qg : kg) + 8 * li;
;             const f32x4 g0 = *(const f32x4*)gp, g1 = *(const f32x4*)(gp + 4);
;             u32x4 o; o.x = pk2(v[0] * rstd * g0.x, v[1] * rstd * g0.y); o.y = pk2(v[2] * rstd * g0.z, v[3] * rstd * g0.w);
;             o.z = pk2(v[4] * rstd * g1.x, v[5] * rstd * g1.y); o.w = pk2(v[6] * rstd * g1.z, v[7] * rstd * g1.w);
;             *(u32x4*)ptr = o;
;         }
	v_add_f32_e32 v238, v238, v239
	ds_bpermute_b32 v239, v205, v238
	s_waitcnt lgkmcnt(0)
	v_add_f32_e32 v238, v238, v239
	ds_bpermute_b32 v239, v214, v238
	s_waitcnt lgkmcnt(0)
	v_add_f32_e32 v238, v238, v239
	ds_bpermute_b32 v239, v215, v238
	s_waitcnt lgkmcnt(0)
	v_add_f32_e32 v238, v238, v239
	v_fmamk_f32 v238, v238, 0x3c000000, v208
	v_mul_f32_e32 v239, 0x4f800000, v238
	v_cmp_gt_f32_e32 vcc, s33, v238
	s_nop 1
	v_cndmask_b32_e32 v238, v238, v239, vcc
	v_sqrt_f32_e32 v239, v238
	s_nop 0
	v_add_u32_e32 v240, -1, v239
	v_add_u32_e32 v241, 1, v239
	v_fma_f32 v242, -v240, v239, v238
	v_fma_f32 v243, -v241, v239, v238
	v_cmp_ge_f32_e64 s[0:1], 0, v242
	s_nop 1
	v_cndmask_b32_e64 v239, v239, v240, s[0:1]
	v_cmp_lt_f32_e64 s[0:1], 0, v243
	s_nop 1
	v_cndmask_b32_e64 v239, v239, v241, s[0:1]
	v_mul_f32_e32 v240, 0x37800000, v239
	v_cndmask_b32_e32 v239, v239, v240, vcc
	v_cmp_class_f32_e32 vcc, v238, v209
	s_nop 1
	v_cndmask_b32_e32 v238, v239, v238, vcc
	v_div_scale_f32 v239, s[0:1], v238, v238, 1.0
	v_rcp_f32_e32 v241, v239
	v_div_scale_f32 v240, vcc, 1.0, v238, 1.0
	v_fma_f32 v242, -v239, v241, 1.0
	v_fmac_f32_e32 v241, v242, v241
	v_mul_f32_e32 v242, v240, v241
	v_fma_f32 v243, -v239, v242, v240
	v_fmac_f32_e32 v242, v243, v241
	v_fma_f32 v239, -v239, v242, v240
	v_div_fmas_f32 v239, v239, v241, v242
	v_div_fixup_f32 v238, v239, v238, 1.0
	v_mul_f32_e32 v217, v217, v238
	v_mul_f32_e32 v80, v217, v80
	v_mul_f32_e32 v81, v217, v81
	v_mul_f32_e32 v82, v217, v82
	v_mul_f32_e32 v83, v217, v83
	v_mul_f32_e32 v234, v217, v234
	v_mul_f32_e32 v235, v217, v235
	v_mul_f32_e32 v236, v217, v236
	v_mul_f32_e32 v237, v217, v237
	v_mul_f32_e32 v80, v219, v80
	v_mul_f32_e32 v81, v221, v81
	v_mul_f32_e32 v82, v223, v82
	v_mul_f32_e32 v83, v225, v83
	v_mul_f32_e32 v244, v218, v234
	v_mul_f32_e32 v245, v220, v235
	v_mul_f32_e32 v246, v222, v236
	v_mul_f32_e32 v247, v224, v237
	v_cvt_pk_bf16_f32 v80, v244, v80
	v_cvt_pk_bf16_f32 v81, v245, v81
	v_cvt_pk_bf16_f32 v82, v246, v82
	v_cvt_pk_bf16_f32 v83, v247, v83
	v_add_u32_e32 v2, 0x200, v216
	v_ashrrev_i32_e32 v3, 31, v2
	v_lshl_add_u64 v[14:15], v[2:3], 1, v[0:1]
	global_store_dwordx4 v[14:15], v[80:83], off
	s_waitcnt vmcnt(19)
	v_mov_b32_e32 v217, v211
	v_lshlrev_b32_e32 v234, 16, v84
	v_and_b32_e32 v84, 0xffff0000, v84
	v_mul_f32_e32 v238, v84, v84
	v_lshlrev_b32_e32 v235, 16, v85
	v_fmac_f32_e32 v238, v234, v234
	v_and_b32_e32 v85, 0xffff0000, v85
	v_fmac_f32_e32 v238, v235, v235
	v_lshlrev_b32_e32 v236, 16, v86
	v_fmac_f32_e32 v238, v85, v85
	v_and_b32_e32 v86, 0xffff0000, v86
	v_fmac_f32_e32 v238, v236, v236
	v_lshlrev_b32_e32 v237, 16, v87
	v_fmac_f32_e32 v238, v86, v86
	v_and_b32_e32 v87, 0xffff0000, v87
	v_fmac_f32_e32 v238, v237, v237
	v_fmac_f32_e32 v238, v87, v87
	ds_bpermute_b32 v239, v204, v238
	s_waitcnt lgkmcnt(0)
	v_add_f32_e32 v238, v238, v239
	ds_bpermute_b32 v239, v205, v238
	s_waitcnt lgkmcnt(0)
	v_add_f32_e32 v238, v238, v239
	ds_bpermute_b32 v239, v214, v238
	s_waitcnt lgkmcnt(0)
	v_add_f32_e32 v238, v238, v239
	ds_bpermute_b32 v239, v215, v238
	s_waitcnt lgkmcnt(0)
	v_add_f32_e32 v238, v238, v239
	v_fmamk_f32 v238, v238, 0x3c000000, v208
	v_mul_f32_e32 v239, 0x4f800000, v238
	v_cmp_gt_f32_e32 vcc, s33, v238
	s_nop 1
	v_cndmask_b32_e32 v238, v238, v239, vcc
	v_sqrt_f32_e32 v239, v238
	s_nop 0
	v_add_u32_e32 v240, -1, v239
	v_add_u32_e32 v241, 1, v239
	v_fma_f32 v242, -v240, v239, v238
	v_fma_f32 v243, -v241, v239, v238
	v_cmp_ge_f32_e64 s[0:1], 0, v242
	s_nop 1
	v_cndmask_b32_e64 v239, v239, v240, s[0:1]
	v_cmp_lt_f32_e64 s[0:1], 0, v243
	s_nop 1
	v_cndmask_b32_e64 v239, v239, v241, s[0:1]
	v_mul_f32_e32 v240, 0x37800000, v239
	v_cndmask_b32_e32 v239, v239, v240, vcc
	v_cmp_class_f32_e32 vcc, v238, v209
	s_nop 1
	v_cndmask_b32_e32 v238, v239, v238, vcc
	v_div_scale_f32 v239, s[0:1], v238, v238, 1.0
	v_rcp_f32_e32 v241, v239
	v_div_scale_f32 v240, vcc, 1.0, v238, 1.0
	v_fma_f32 v242, -v239, v241, 1.0
	v_fmac_f32_e32 v241, v242, v241
	v_mul_f32_e32 v242, v240, v241
	v_fma_f32 v243, -v239, v242, v240
	v_fmac_f32_e32 v242, v243, v241
	v_fma_f32 v239, -v239, v242, v240
	v_div_fmas_f32 v239, v239, v241, v242
	v_div_fixup_f32 v238, v239, v238, 1.0
	v_mul_f32_e32 v217, v217, v238
	v_mul_f32_e32 v84, v217, v84
	v_mul_f32_e32 v85, v217, v85
	v_mul_f32_e32 v86, v217, v86
	v_mul_f32_e32 v87, v217, v87
	v_mul_f32_e32 v234, v217, v234
	v_mul_f32_e32 v235, v217, v235
	v_mul_f32_e32 v236, v217, v236
	v_mul_f32_e32 v237, v217, v237
	v_mul_f32_e32 v84, v219, v84
	v_mul_f32_e32 v85, v221, v85
	v_mul_f32_e32 v86, v223, v86
	v_mul_f32_e32 v87, v225, v87
	v_mul_f32_e32 v244, v218, v234
	v_mul_f32_e32 v245, v220, v235
	v_mul_f32_e32 v246, v222, v236
	v_mul_f32_e32 v247, v224, v237
	v_cvt_pk_bf16_f32 v84, v244, v84
	v_cvt_pk_bf16_f32 v85, v245, v85
	v_cvt_pk_bf16_f32 v86, v246, v86
	v_cvt_pk_bf16_f32 v87, v247, v87
	v_add_u32_e32 v2, 0x400, v216
	v_ashrrev_i32_e32 v3, 31, v2
	v_lshl_add_u64 v[14:15], v[2:3], 1, v[0:1]
	global_store_dwordx4 v[14:15], v[84:87], off
	s_waitcnt vmcnt(19)
	v_mov_b32_e32 v217, v211
	v_lshlrev_b32_e32 v234, 16, v88
	v_and_b32_e32 v88, 0xffff0000, v88
	v_mul_f32_e32 v238, v88, v88
	v_lshlrev_b32_e32 v235, 16, v89
	v_fmac_f32_e32 v238, v234, v234
	v_and_b32_e32 v89, 0xffff0000, v89
	v_fmac_f32_e32 v238, v235, v235
	v_lshlrev_b32_e32 v236, 16, v90
	v_fmac_f32_e32 v238, v89, v89
	v_and_b32_e32 v90, 0xffff0000, v90
	v_fmac_f32_e32 v238, v236, v236
	v_lshlrev_b32_e32 v237, 16, v91
	v_fmac_f32_e32 v238, v90, v90
	v_and_b32_e32 v91, 0xffff0000, v91
	v_fmac_f32_e32 v238, v237, v237
	v_fmac_f32_e32 v238, v91, v91
	ds_bpermute_b32 v239, v204, v238
	s_waitcnt lgkmcnt(0)
; __device__ __forceinline__ unsigned pk2(float lo, float hi) { return pg8::cvt_pk_bf16(lo, hi); }
; __device__ __forceinline__ void idx_unit(bf16* QB, float* SC, int* SEL, const float* qg, const float* kg, int b, int tp, LAS unsigned char* wl, int lane, bool do_norm) {
;     ...
;             const u32x4 w = *(const u32x4*)ptr;
;             float v[8] = {bflo(w.x), bfhi(w.x), bflo(w.y), bfhi(w.y), bflo(w.z), bfhi(w.z), bflo(w.w), bfhi(w.w)};
;             float s = 0.f;
; #pragma unroll
;             for (int e = 0; e < 8; ++e) s += v[e] * v[e];
;             s += __shfl_xor(s, 1); s += __shfl_xor(s, 2); s += __shfl_xor(s, 4); s += __shfl_xor(s, 8);
;             const float rstd = (1.0f / sqrtf(s * (1.f / 128.f) + RMS_EPS)) * ((p < 4) ? C2 : 1.f);
;             const float* gp = ((p < 4) ? qg : kg) + 8 * li;
;             const f32x4 g0 = *(const f32x4*)gp, g1 = *(const f32x4*)(gp + 4);
;             u32x4 o; o.x = pk2(v[0] * rstd * g0.x, v[1] * rstd * g0.y); o.y = pk2(v[2] * rstd * g0.z, v[3] * rstd * g0.w);
;             o.z = pk2(v[4] * rstd * g1.x, v[5] * rstd * g1.y); o.w = pk2(v[6] * rstd * g1.z, v[7] * rstd * g1.w);
;             *(u32x4*)ptr = o;
;         }
; __global__ void __launch_bounds__(NWAVES * 64, 2) fwd_megakernel(Args args) {
;     ...
;                 for (int rep = 0; rep < REP_IDX; ++rep) for (int i = 0; i * ngw < NBATCH * per; ++i) { const int u = i * ngw + gw; if (u >= NBATCH * per) break;
	v_add_f32_e32 v238, v238, v239
	ds_bpermute_b32 v239, v205, v238
	s_waitcnt lgkmcnt(0)
	v_add_f32_e32 v238, v238, v239
	ds_bpermute_b32 v239, v214, v238
	s_waitcnt lgkmcnt(0)
	v_add_f32_e32 v238, v238, v239
	ds_bpermute_b32 v239, v215, v238
	s_waitcnt lgkmcnt(0)
	v_add_f32_e32 v238, v238, v239
	v_fmamk_f32 v238, v238, 0x3c000000, v208
	v_mul_f32_e32 v239, 0x4f800000, v238
	v_cmp_gt_f32_e32 vcc, s33, v238
	s_nop 1
	v_cndmask_b32_e32 v238, v238, v239, vcc
	v_sqrt_f32_e32 v239, v238
	s_nop 0
	v_add_u32_e32 v240, -1, v239
	v_add_u32_e32 v241, 1, v239
	v_fma_f32 v242, -v240, v239, v238
	v_fma_f32 v243, -v241, v239, v238
	v_cmp_ge_f32_e64 s[0:1], 0, v242
	s_nop 1
	v_cndmask_b32_e64 v239, v239, v240, s[0:1]
	v_cmp_lt_f32_e64 s[0:1], 0, v243
	s_nop 1
	v_cndmask_b32_e64 v239, v239, v241, s[0:1]
	v_mul_f32_e32 v240, 0x37800000, v239
	v_cndmask_b32_e32 v239, v239, v240, vcc
	v_cmp_class_f32_e32 vcc, v238, v209
	s_nop 1
	v_cndmask_b32_e32 v238, v239, v238, vcc
	v_div_scale_f32 v239, s[0:1], v238, v238, 1.0
	v_rcp_f32_e32 v241, v239
	v_div_scale_f32 v240, vcc, 1.0, v238, 1.0
	v_fma_f32 v242, -v239, v241, 1.0
	v_fmac_f32_e32 v241, v242, v241
	v_mul_f32_e32 v242, v240, v241
	v_fma_f32 v243, -v239, v242, v240
	v_fmac_f32_e32 v242, v243, v241
	v_fma_f32 v239, -v239, v242, v240
	v_div_fmas_f32 v239, v239, v241, v242
	v_div_fixup_f32 v238, v239, v238, 1.0
	v_mul_f32_e32 v217, v217, v238
	v_mul_f32_e32 v88, v217, v88
	v_mul_f32_e32 v89, v217, v89
	v_mul_f32_e32 v90, v217, v90
	v_mul_f32_e32 v91, v217, v91
	v_mul_f32_e32 v234, v217, v234
	v_mul_f32_e32 v235, v217, v235
	v_mul_f32_e32 v236, v217, v236
	v_mul_f32_e32 v237, v217, v237
	v_mul_f32_e32 v88, v219, v88
	v_mul_f32_e32 v89, v221, v89
	v_mul_f32_e32 v90, v223, v90
	v_mul_f32_e32 v91, v225, v91
	v_mul_f32_e32 v244, v218, v234
	v_mul_f32_e32 v245, v220, v235
	v_mul_f32_e32 v246, v222, v236
	v_mul_f32_e32 v247, v224, v237
	v_cvt_pk_bf16_f32 v88, v244, v88
	v_cvt_pk_bf16_f32 v89, v245, v89
	v_cvt_pk_bf16_f32 v90, v246, v90
	v_cvt_pk_bf16_f32 v91, v247, v91
	v_add_u32_e32 v2, 0x600, v216
	v_ashrrev_i32_e32 v3, 31, v2
	v_lshl_add_u64 v[14:15], v[2:3], 1, v[0:1]
	global_store_dwordx4 v[14:15], v[88:91], off
	s_waitcnt vmcnt(19)
	v_mov_b32_e32 v217, 1.0
	v_lshlrev_b32_e32 v234, 16, v92
	v_and_b32_e32 v92, 0xffff0000, v92
	v_mul_f32_e32 v238, v92, v92
	v_lshlrev_b32_e32 v235, 16, v93
	v_fmac_f32_e32 v238, v234, v234
	v_and_b32_e32 v93, 0xffff0000, v93
	v_fmac_f32_e32 v238, v235, v235
	v_lshlrev_b32_e32 v236, 16, v94
	v_fmac_f32_e32 v238, v93, v93
	v_and_b32_e32 v94, 0xffff0000, v94
	v_fmac_f32_e32 v238, v236, v236
	v_lshlrev_b32_e32 v237, 16, v95
	v_fmac_f32_e32 v238, v94, v94
	v_and_b32_e32 v95, 0xffff0000, v95
	v_fmac_f32_e32 v238, v237, v237
	v_fmac_f32_e32 v238, v95, v95
	ds_bpermute_b32 v239, v204, v238
	s_waitcnt lgkmcnt(0)
	v_add_f32_e32 v238, v238, v239
	ds_bpermute_b32 v239, v205, v238
	s_waitcnt lgkmcnt(0)
	v_add_f32_e32 v238, v238, v239
	ds_bpermute_b32 v239, v214, v238
	s_waitcnt lgkmcnt(0)
	v_add_f32_e32 v238, v238, v239
	ds_bpermute_b32 v239, v215, v238
	s_waitcnt lgkmcnt(0)
	v_add_f32_e32 v238, v238, v239
	v_fmamk_f32 v238, v238, 0x3c000000, v208
	v_mul_f32_e32 v239, 0x4f800000, v238
	v_cmp_gt_f32_e32 vcc, s33, v238
	s_nop 1
	v_cndmask_b32_e32 v238, v238, v239, vcc
	v_sqrt_f32_e32 v239, v238
	s_nop 0
	v_add_u32_e32 v240, -1, v239
	v_add_u32_e32 v241, 1, v239
	v_fma_f32 v242, -v240, v239, v238
	v_fma_f32 v243, -v241, v239, v238
	v_cmp_ge_f32_e64 s[0:1], 0, v242
	s_nop 1
	v_cndmask_b32_e64 v239, v239, v240, s[0:1]
	v_cmp_lt_f32_e64 s[0:1], 0, v243
	s_nop 1
	v_cndmask_b32_e64 v239, v239, v241, s[0:1]
	v_mul_f32_e32 v240, 0x37800000, v239
	v_cndmask_b32_e32 v239, v239, v240, vcc
	v_cmp_class_f32_e32 vcc, v238, v209
	s_nop 1
	v_cndmask_b32_e32 v238, v239, v238, vcc
	v_div_scale_f32 v239, s[0:1], v238, v238, 1.0
	v_rcp_f32_e32 v241, v239
	v_div_scale_f32 v240, vcc, 1.0, v238, 1.0
	v_fma_f32 v242, -v239, v241, 1.0
	v_fmac_f32_e32 v241, v242, v241
	v_mul_f32_e32 v242, v240, v241
	v_fma_f32 v243, -v239, v242, v240
	v_fmac_f32_e32 v242, v243, v241
	v_fma_f32 v239, -v239, v242, v240
	v_div_fmas_f32 v239, v239, v241, v242
	v_div_fixup_f32 v238, v239, v238, 1.0
	v_mul_f32_e32 v217, v217, v238
	v_mul_f32_e32 v92, v217, v92
	v_mul_f32_e32 v93, v217, v93
	v_mul_f32_e32 v94, v217, v94
	v_mul_f32_e32 v95, v217, v95
	v_mul_f32_e32 v234, v217, v234
	v_mul_f32_e32 v235, v217, v235
	v_mul_f32_e32 v236, v217, v236
	v_mul_f32_e32 v237, v217, v237
	v_mul_f32_e32 v92, v227, v92
	v_mul_f32_e32 v93, v229, v93
	v_mul_f32_e32 v94, v231, v94
	v_mul_f32_e32 v95, v233, v95
	v_mul_f32_e32 v244, v226, v234
	v_mul_f32_e32 v245, v228, v235
	v_mul_f32_e32 v246, v230, v236
	v_mul_f32_e32 v247, v232, v237
	v_cvt_pk_bf16_f32 v92, v244, v92
	v_cvt_pk_bf16_f32 v93, v245, v93
	v_cvt_pk_bf16_f32 v94, v246, v94
	v_cvt_pk_bf16_f32 v95, v247, v95
	v_add_u32_e32 v2, 0x800, v216
	v_ashrrev_i32_e32 v3, 31, v2
	v_lshl_add_u64 v[14:15], v[2:3], 1, v[0:1]
	global_store_dwordx4 v[14:15], v[92:95], off
	s_mov_b32 s3, 4
	s_add_i32 s11, s11, 1
	s_mul_i32 s2, s11, s84
	s_cmpk_gt_i32 s2, 0xfff
	v_readlane_b32 s78, v253, 53
	s_cselect_b64 s[0:1], -1, 0
	s_mov_b64 s[0:1], 0
	v_readlane_b32 s79, v253, 54
	s_movk_i32 s90, 0x2000
	s_movk_i32 s91, 0x2200
	s_mov_b64 s[96:97], 0x2000
	s_branch .LBB0_229
